# v55 plus loop-edge edit: K-loop scalar back-edge bookkeeping moved from the head of the load segment to the end of the preceding MFMA burst, in front of its barrier
# baseline (speedup 1.0000x reference)
; #define PG8_STAGE(bufoff, gbase, voff) do { _Pragma("unroll") for (int _i = 0; _i < 2; ++_i) \
;         __builtin_amdgcn_global_load_lds((const unsigned*)((const char*)(gbase) + (voff)[_i]), (PG8_LAS unsigned*)(lds + (bufoff) + ldsw + _i * 8192), 16, 0, 0); } while (0)
; #define PG8_LDA(dst, b, h) do { _Pragma("unroll") for (int m = 0; m < 4; ++m) _Pragma("unroll") for (int k = 0; k < 2; ++k) dst[m][k] = *(const PG8_LAS bf16x8*)(lds + PG8_SA(b, h) + aoff + m * 2048 + k * 1024); } while (0)
; #define PG8_LDB(dst, b, h) do { _Pragma("unroll") for (int n = 0; n < 2; ++n) _Pragma("unroll") for (int k = 0; k < 2; ++k) dst[n][k] = *(const PG8_LAS bf16x8*)(lds + PG8_SB(b, h) + boff + n * 2048 + k * 1024); } while (0)
; #define PG8_MMA(ai, bj, At, Bt) do { __builtin_amdgcn_s_setprio(1); _Pragma("unroll") for (int m = 0; m < 4; ++m) _Pragma("unroll") for (int n = 0; n < 2; ++n) _Pragma("unroll") for (int k = 0; k < 2; ++k) \
;         acc[ai][bj][m][n] = __builtin_amdgcn_mfma_f32_16x16x32_bf16(Bt[n][k], At[m][k], acc[ai][bj][m][n], 0, 0, 0); __builtin_amdgcn_s_setprio(0); } while (0)
; #define PG8_WAIT_V(n) asm volatile("s_waitcnt vmcnt(" #n ")" ::: "memory")
; #define PG8_WAIT_L(n) asm volatile("s_waitcnt lgkmcnt(" #n ")" ::: "memory")
; #define PG8_BAR __builtin_amdgcn_s_barrier()
; #define PG8_SCHED __builtin_amdgcn_sched_barrier(0)
; template <class Epi, class Sched, bool ALIGN_EPI = false, bool SP2 = false>
; __device__ __forceinline__ void gemm_phase(PG8_LAS unsigned char* lds, const Gemm g, const Sched& S, const Epi& E) {
;     ...
;             PG8_LDB(B0, 0, 0); PG8_LDB(B1, 0, 1); PG8_SCHED; PG8_LDA(At, 0, 0); PG8_STAGE(PG8_SA(1, 1), a1 + hstep, voffA);
;             PG8_WAIT_V(8); PG8_WAIT_L(0); PG8_BAR; PG8_MMA(0, 0, At, B0); PG8_MMA(0, 1, At, B1); PG8_BAR; PG8_SCHED;
;             PG8_LDA(At, 0, 1); PG8_STAGE(PG8_SB(0, 0), b2, voffB); PG8_STAGE(PG8_SB(0, 1), b2 + hstep, voffB); PG8_STAGE(PG8_SA(0, 0), a2, voffA);
;             PG8_WAIT_V(8); PG8_WAIT_L(0); PG8_BAR; PG8_MMA(1, 0, At, B0); PG8_MMA(1, 1, At, B1); PG8_BAR; PG8_SCHED;
.LBB0_301:
	ds_read_b128 v[174:177], v249 offset:16384
	ds_read_b128 v[178:181], v249 offset:17408
	ds_read_b128 v[204:207], v249 offset:18432
	ds_read_b128 v[208:211], v249 offset:19456
	s_add_i32 m0, s47, 0xc000
	ds_read_b128 v[212:215], v153
	ds_read_b128 v[216:219], v153 offset:1024
	ds_read_b128 v[220:223], v153 offset:2048
	ds_read_b128 v[224:227], v153 offset:3072
	ds_read_b128 v[228:231], v153 offset:4096
	ds_read_b128 v[232:235], v153 offset:5120
	ds_read_b128 v[236:239], v153 offset:6144
	ds_read_b128 v[240:243], v153 offset:7168
	global_load_lds_dwordx4 v138, s[36:37]
	s_add_i32 m0, s47, 0xe000
	s_nop 0
	global_load_lds_dwordx4 v140, s[36:37]
	s_waitcnt vmcnt(8) lgkmcnt(0)
	s_setprio 0
	s_barrier
	v_mfma_f32_16x16x32_bf16 v[128:131], v[142:145], v[212:215], v[128:131]
	v_mfma_f32_16x16x32_bf16 v[120:123], v[154:157], v[212:215], v[120:123]
	v_mfma_f32_16x16x32_bf16 v[112:115], v[142:145], v[220:223], v[112:115]
	v_mfma_f32_16x16x32_bf16 v[104:107], v[154:157], v[220:223], v[104:107]
	v_mfma_f32_16x16x32_bf16 v[96:99], v[142:145], v[228:231], v[96:99]
	v_mfma_f32_16x16x32_bf16 v[88:91], v[154:157], v[228:231], v[88:91]
	v_mfma_f32_16x16x32_bf16 v[80:83], v[142:145], v[236:239], v[80:83]
	v_mfma_f32_16x16x32_bf16 v[72:75], v[154:157], v[236:239], v[72:75]
	v_mfma_f32_16x16x32_bf16 v[128:131], v[146:149], v[216:219], v[128:131]
	v_mfma_f32_16x16x32_bf16 v[120:123], v[158:161], v[216:219], v[120:123]
	v_mfma_f32_16x16x32_bf16 v[112:115], v[146:149], v[224:227], v[112:115]
	v_mfma_f32_16x16x32_bf16 v[104:107], v[158:161], v[224:227], v[104:107]
	v_mfma_f32_16x16x32_bf16 v[96:99], v[146:149], v[232:235], v[96:99]
	v_mfma_f32_16x16x32_bf16 v[88:91], v[158:161], v[232:235], v[88:91]
	v_mfma_f32_16x16x32_bf16 v[80:83], v[146:149], v[240:243], v[80:83]
	v_mfma_f32_16x16x32_bf16 v[72:75], v[158:161], v[240:243], v[72:75]
	v_mfma_f32_16x16x32_bf16 v[124:127], v[174:177], v[212:215], v[124:127]
	v_mfma_f32_16x16x32_bf16 v[116:119], v[204:207], v[212:215], v[116:119]
	v_mfma_f32_16x16x32_bf16 v[108:111], v[174:177], v[220:223], v[108:111]
	v_mfma_f32_16x16x32_bf16 v[100:103], v[204:207], v[220:223], v[100:103]
	v_mfma_f32_16x16x32_bf16 v[92:95], v[174:177], v[228:231], v[92:95]
	v_mfma_f32_16x16x32_bf16 v[84:87], v[204:207], v[228:231], v[84:87]
	v_mfma_f32_16x16x32_bf16 v[76:79], v[174:177], v[236:239], v[76:79]
	v_mfma_f32_16x16x32_bf16 v[68:71], v[204:207], v[236:239], v[68:71]
	v_mfma_f32_16x16x32_bf16 v[124:127], v[178:181], v[216:219], v[124:127]
	v_mfma_f32_16x16x32_bf16 v[116:119], v[208:211], v[216:219], v[116:119]
	v_mfma_f32_16x16x32_bf16 v[108:111], v[178:181], v[224:227], v[108:111]
	v_mfma_f32_16x16x32_bf16 v[100:103], v[208:211], v[224:227], v[100:103]
	v_mfma_f32_16x16x32_bf16 v[92:95], v[178:181], v[232:235], v[92:95]
	v_mfma_f32_16x16x32_bf16 v[84:87], v[208:211], v[232:235], v[84:87]
	v_mfma_f32_16x16x32_bf16 v[76:79], v[178:181], v[240:243], v[76:79]
	v_mfma_f32_16x16x32_bf16 v[68:71], v[208:211], v[240:243], v[68:71]
	s_setprio 3
	s_barrier
	s_add_i32 s61, s61, s42
	s_mov_b32 m0, s61
	ds_read_b128 v[212:215], v153 offset:16384
	ds_read_b128 v[216:219], v153 offset:17408
	ds_read_b128 v[220:223], v153 offset:18432
	ds_read_b128 v[224:227], v153 offset:19456
	ds_read_b128 v[228:231], v153 offset:20480
	ds_read_b128 v[232:235], v153 offset:21504
	ds_read_b128 v[236:239], v153 offset:22528
	ds_read_b128 v[240:243], v153 offset:23552
	global_load_lds_dwordx4 v2, s[38:39]
	s_add_i32 m0, s61, 0x2000
	s_add_u32 s62, s38, 0x80000
	s_addc_u32 s63, s39, 0
	s_add_i32 s61, s64, s42
	global_load_lds_dwordx4 v132, s[38:39]
	s_mov_b32 m0, s61
	s_nop 0
	global_load_lds_dwordx4 v2, s[62:63]
	s_add_i32 m0, s61, 0x2000
	s_nop 0
	global_load_lds_dwordx4 v132, s[62:63]
	s_mov_b32 m0, s47
	s_nop 0
	global_load_lds_dwordx4 v136, s[40:41]
	s_mov_b32 m0, s48
	s_nop 0
	global_load_lds_dwordx4 v134, s[40:41]
	s_waitcnt vmcnt(8) lgkmcnt(0)
	s_setprio 0
	s_barrier
	v_mfma_f32_16x16x32_bf16 v[64:67], v[142:145], v[212:215], v[64:67]
	v_mfma_f32_16x16x32_bf16 v[56:59], v[154:157], v[212:215], v[56:59]
	v_mfma_f32_16x16x32_bf16 v[48:51], v[142:145], v[220:223], v[48:51]
	v_mfma_f32_16x16x32_bf16 v[40:43], v[154:157], v[220:223], v[40:43]
	v_mfma_f32_16x16x32_bf16 v[32:35], v[142:145], v[228:231], v[32:35]
	v_mfma_f32_16x16x32_bf16 v[24:27], v[154:157], v[228:231], v[24:27]
	v_mfma_f32_16x16x32_bf16 v[16:19], v[142:145], v[236:239], v[16:19]
	v_mfma_f32_16x16x32_bf16 v[8:11], v[154:157], v[236:239], v[8:11]
	v_mfma_f32_16x16x32_bf16 v[64:67], v[146:149], v[216:219], v[64:67]
	v_mfma_f32_16x16x32_bf16 v[56:59], v[158:161], v[216:219], v[56:59]
	v_mfma_f32_16x16x32_bf16 v[48:51], v[146:149], v[224:227], v[48:51]
	v_mfma_f32_16x16x32_bf16 v[40:43], v[158:161], v[224:227], v[40:43]
	v_mfma_f32_16x16x32_bf16 v[32:35], v[146:149], v[232:235], v[32:35]
	v_mfma_f32_16x16x32_bf16 v[24:27], v[158:161], v[232:235], v[24:27]
	v_mfma_f32_16x16x32_bf16 v[16:19], v[146:149], v[240:243], v[16:19]
	v_mfma_f32_16x16x32_bf16 v[8:11], v[158:161], v[240:243], v[8:11]
	v_mfma_f32_16x16x32_bf16 v[60:63], v[174:177], v[212:215], v[60:63]
	ds_read_b128 v[142:145], v249 offset:32768
	v_mfma_f32_16x16x32_bf16 v[52:55], v[204:207], v[212:215], v[52:55]
	ds_read_b128 v[146:149], v249 offset:33792
	v_mfma_f32_16x16x32_bf16 v[44:47], v[174:177], v[220:223], v[44:47]
	ds_read_b128 v[154:157], v249 offset:34816
	v_mfma_f32_16x16x32_bf16 v[36:39], v[204:207], v[220:223], v[36:39]
	ds_read_b128 v[158:161], v249 offset:35840
	v_mfma_f32_16x16x32_bf16 v[28:31], v[174:177], v[228:231], v[28:31]
	v_mfma_f32_16x16x32_bf16 v[20:23], v[204:207], v[228:231], v[20:23]
	v_mfma_f32_16x16x32_bf16 v[12:15], v[174:177], v[236:239], v[12:15]
	v_mfma_f32_16x16x32_bf16 v[4:7], v[204:207], v[236:239], v[4:7]
	v_mfma_f32_16x16x32_bf16 v[60:63], v[178:181], v[216:219], v[60:63]
	v_mfma_f32_16x16x32_bf16 v[52:55], v[208:211], v[216:219], v[52:55]
	v_mfma_f32_16x16x32_bf16 v[44:47], v[178:181], v[224:227], v[44:47]
	v_mfma_f32_16x16x32_bf16 v[36:39], v[208:211], v[224:227], v[36:39]
	v_mfma_f32_16x16x32_bf16 v[28:31], v[178:181], v[232:235], v[28:31]
	v_mfma_f32_16x16x32_bf16 v[20:23], v[208:211], v[232:235], v[20:23]
	v_mfma_f32_16x16x32_bf16 v[12:15], v[178:181], v[240:243], v[12:15]
	v_mfma_f32_16x16x32_bf16 v[4:7], v[208:211], v[240:243], v[4:7]
	s_setprio 3
	s_barrier
; #define PG8_STAGE(bufoff, gbase, voff) do { _Pragma("unroll") for (int _i = 0; _i < 2; ++_i) \
;         __builtin_amdgcn_global_load_lds((const unsigned*)((const char*)(gbase) + (voff)[_i]), (PG8_LAS unsigned*)(lds + (bufoff) + ldsw + _i * 8192), 16, 0, 0); } while (0)
; #define PG8_LDA(dst, b, h) do { _Pragma("unroll") for (int m = 0; m < 4; ++m) _Pragma("unroll") for (int k = 0; k < 2; ++k) dst[m][k] = *(const PG8_LAS bf16x8*)(lds + PG8_SA(b, h) + aoff + m * 2048 + k * 1024); } while (0)
; #define PG8_LDB(dst, b, h) do { _Pragma("unroll") for (int n = 0; n < 2; ++n) _Pragma("unroll") for (int k = 0; k < 2; ++k) dst[n][k] = *(const PG8_LAS bf16x8*)(lds + PG8_SB(b, h) + boff + n * 2048 + k * 1024); } while (0)
; #define PG8_MMA(ai, bj, At, Bt) do { __builtin_amdgcn_s_setprio(1); _Pragma("unroll") for (int m = 0; m < 4; ++m) _Pragma("unroll") for (int n = 0; n < 2; ++n) _Pragma("unroll") for (int k = 0; k < 2; ++k) \
;         acc[ai][bj][m][n] = __builtin_amdgcn_mfma_f32_16x16x32_bf16(Bt[n][k], At[m][k], acc[ai][bj][m][n], 0, 0, 0); __builtin_amdgcn_s_setprio(0); } while (0)
; #define PG8_WAIT_V(n) asm volatile("s_waitcnt vmcnt(" #n ")" ::: "memory")
; #define PG8_WAIT_L(n) asm volatile("s_waitcnt lgkmcnt(" #n ")" ::: "memory")
; template <class Epi, class Sched, bool ALIGN_EPI = false, bool SP2 = false>
; __device__ __forceinline__ void gemm_phase(PG8_LAS unsigned char* lds, const Gemm g, const Sched& S, const Epi& E) {
;     ...
;         for (int t = 0; t < nt; t += 2) {
;             const bool last = (t == nt - 2);
;             const char* a1 = cA + (size_t)(t + 1) * kstep;
;             const char* a2 = last ? nA : cA + (size_t)(t + 2) * kstep; const char* b2 = last ? nB : cB + (size_t)(t + 2) * kstep;
;             const char* a3 = a2 + kstep; const char* b3 = b2 + kstep;
;             if (last && has_next) S.a_ready(nxt);
;     ...
;             PG8_LDB(B0, 1, 0); PG8_LDB(B1, 1, 1); PG8_SCHED; PG8_LDA(At, 1, 0); PG8_STAGE(PG8_SA(0, 1), a2 + hstep, voffA);
;             PG8_WAIT_V(8); PG8_WAIT_L(0); PG8_BAR; PG8_MMA(0, 0, At, B0); PG8_MMA(0, 1, At, B1); PG8_BAR; PG8_SCHED;
;             PG8_LDA(At, 1, 1); PG8_STAGE(PG8_SB(1, 0), b3, voffB); PG8_STAGE(PG8_SB(1, 1), b3 + hstep, voffB); PG8_STAGE(PG8_SA(1, 0), a3, voffA);
;             PG8_WAIT_V(8); PG8_WAIT_L(0); PG8_BAR; PG8_MMA(1, 0, At, B0); PG8_MMA(1, 1, At, B1); PG8_BAR; PG8_SCHED;
	s_add_i32 s61, 0, 0x18000
	s_add_i32 s62, 0, 0x1c000
	ds_read_b128 v[174:177], v249 offset:49152
	ds_read_b128 v[178:181], v249 offset:50176
	ds_read_b128 v[204:207], v249 offset:51200
	ds_read_b128 v[208:211], v249 offset:52224
	s_add_u32 s100, s40, 0x80
	s_addc_u32 s101, s41, 0
	s_add_u32 s40, s40, 0x80000
	s_addc_u32 s41, s41, 0
	s_mov_b32 m0, s49
	ds_read_b128 v[212:215], v153 offset:32768
	ds_read_b128 v[216:219], v153 offset:33792
	ds_read_b128 v[220:223], v153 offset:34816
	ds_read_b128 v[224:227], v153 offset:35840
	ds_read_b128 v[228:231], v153 offset:36864
	ds_read_b128 v[232:235], v153 offset:37888
	ds_read_b128 v[236:239], v153 offset:38912
	ds_read_b128 v[240:243], v153 offset:39936
	global_load_lds_dwordx4 v136, s[40:41]
	s_mov_b32 m0, s50
	s_nop 0
	global_load_lds_dwordx4 v134, s[40:41]
	s_waitcnt vmcnt(8) lgkmcnt(0)
	s_setprio 0
	s_barrier
	v_mfma_f32_16x16x32_bf16 v[128:131], v[142:145], v[212:215], v[128:131]
	v_mfma_f32_16x16x32_bf16 v[120:123], v[154:157], v[212:215], v[120:123]
	v_mfma_f32_16x16x32_bf16 v[112:115], v[142:145], v[220:223], v[112:115]
	v_mfma_f32_16x16x32_bf16 v[104:107], v[154:157], v[220:223], v[104:107]
	v_mfma_f32_16x16x32_bf16 v[96:99], v[142:145], v[228:231], v[96:99]
	v_mfma_f32_16x16x32_bf16 v[88:91], v[154:157], v[228:231], v[88:91]
	v_mfma_f32_16x16x32_bf16 v[80:83], v[142:145], v[236:239], v[80:83]
	v_mfma_f32_16x16x32_bf16 v[72:75], v[154:157], v[236:239], v[72:75]
	v_mfma_f32_16x16x32_bf16 v[128:131], v[146:149], v[216:219], v[128:131]
	v_mfma_f32_16x16x32_bf16 v[120:123], v[158:161], v[216:219], v[120:123]
	v_mfma_f32_16x16x32_bf16 v[112:115], v[146:149], v[224:227], v[112:115]
	v_mfma_f32_16x16x32_bf16 v[104:107], v[158:161], v[224:227], v[104:107]
	v_mfma_f32_16x16x32_bf16 v[96:99], v[146:149], v[232:235], v[96:99]
	v_mfma_f32_16x16x32_bf16 v[88:91], v[158:161], v[232:235], v[88:91]
	v_mfma_f32_16x16x32_bf16 v[80:83], v[146:149], v[240:243], v[80:83]
	v_mfma_f32_16x16x32_bf16 v[72:75], v[158:161], v[240:243], v[72:75]
	v_mfma_f32_16x16x32_bf16 v[124:127], v[174:177], v[212:215], v[124:127]
	v_mfma_f32_16x16x32_bf16 v[116:119], v[204:207], v[212:215], v[116:119]
	v_mfma_f32_16x16x32_bf16 v[108:111], v[174:177], v[220:223], v[108:111]
	v_mfma_f32_16x16x32_bf16 v[100:103], v[204:207], v[220:223], v[100:103]
	v_mfma_f32_16x16x32_bf16 v[92:95], v[174:177], v[228:231], v[92:95]
	v_mfma_f32_16x16x32_bf16 v[84:87], v[204:207], v[228:231], v[84:87]
	v_mfma_f32_16x16x32_bf16 v[76:79], v[174:177], v[236:239], v[76:79]
	v_mfma_f32_16x16x32_bf16 v[68:71], v[204:207], v[236:239], v[68:71]
	v_mfma_f32_16x16x32_bf16 v[124:127], v[178:181], v[216:219], v[124:127]
	v_mfma_f32_16x16x32_bf16 v[116:119], v[208:211], v[216:219], v[116:119]
	v_mfma_f32_16x16x32_bf16 v[108:111], v[178:181], v[224:227], v[108:111]
	v_mfma_f32_16x16x32_bf16 v[100:103], v[208:211], v[224:227], v[100:103]
	v_mfma_f32_16x16x32_bf16 v[92:95], v[178:181], v[232:235], v[92:95]
	v_mfma_f32_16x16x32_bf16 v[84:87], v[208:211], v[232:235], v[84:87]
	v_mfma_f32_16x16x32_bf16 v[76:79], v[178:181], v[240:243], v[76:79]
	v_mfma_f32_16x16x32_bf16 v[68:71], v[208:211], v[240:243], v[68:71]
	s_setprio 3
	s_barrier
	s_add_i32 s40, s61, s42
	s_add_i32 m0, s40, 0xffffff80
	ds_read_b128 v[212:215], v153 offset:49152
	ds_read_b128 v[216:219], v153 offset:50176
	ds_read_b128 v[220:223], v153 offset:51200
	ds_read_b128 v[224:227], v153 offset:52224
	ds_read_b128 v[228:231], v153 offset:53248
	ds_read_b128 v[232:235], v153 offset:54272
	ds_read_b128 v[236:239], v153 offset:55296
	ds_read_b128 v[240:243], v153 offset:56320
	global_load_lds_dwordx4 v2, s[38:39] offset:128
	s_add_i32 m0, s40, 0x1f80
	s_add_i32 s40, s62, s42
	global_load_lds_dwordx4 v132, s[38:39] offset:128
	s_add_u32 s38, s38, 0x80080
	s_addc_u32 s39, s39, 0
	s_mov_b32 m0, s40
	s_nop 0
	global_load_lds_dwordx4 v2, s[38:39]
	s_add_i32 m0, s40, 0x2000
	s_nop 0
	global_load_lds_dwordx4 v132, s[38:39]
	s_mov_b32 m0, s51
	s_nop 0
	global_load_lds_dwordx4 v136, s[100:101]
	s_mov_b32 m0, s53
	s_nop 0
	global_load_lds_dwordx4 v134, s[100:101]
	s_nop 0
	s_waitcnt vmcnt(8) lgkmcnt(0)
	s_setprio 0
	s_barrier
	v_mfma_f32_16x16x32_bf16 v[64:67], v[142:145], v[212:215], v[64:67]
	v_mfma_f32_16x16x32_bf16 v[56:59], v[154:157], v[212:215], v[56:59]
	v_mfma_f32_16x16x32_bf16 v[48:51], v[142:145], v[220:223], v[48:51]
	v_mfma_f32_16x16x32_bf16 v[40:43], v[154:157], v[220:223], v[40:43]
	v_mfma_f32_16x16x32_bf16 v[32:35], v[142:145], v[228:231], v[32:35]
	v_mfma_f32_16x16x32_bf16 v[24:27], v[154:157], v[228:231], v[24:27]
	v_mfma_f32_16x16x32_bf16 v[16:19], v[142:145], v[236:239], v[16:19]
	v_mfma_f32_16x16x32_bf16 v[8:11], v[154:157], v[236:239], v[8:11]
	v_mfma_f32_16x16x32_bf16 v[64:67], v[146:149], v[216:219], v[64:67]
	v_mfma_f32_16x16x32_bf16 v[56:59], v[158:161], v[216:219], v[56:59]
	v_mfma_f32_16x16x32_bf16 v[48:51], v[146:149], v[224:227], v[48:51]
	v_mfma_f32_16x16x32_bf16 v[40:43], v[158:161], v[224:227], v[40:43]
	v_mfma_f32_16x16x32_bf16 v[32:35], v[146:149], v[232:235], v[32:35]
	v_mfma_f32_16x16x32_bf16 v[24:27], v[158:161], v[232:235], v[24:27]
	v_mfma_f32_16x16x32_bf16 v[16:19], v[146:149], v[240:243], v[16:19]
	v_mfma_f32_16x16x32_bf16 v[8:11], v[158:161], v[240:243], v[8:11]
	v_mfma_f32_16x16x32_bf16 v[60:63], v[174:177], v[212:215], v[60:63]
	ds_read_b128 v[142:145], v249
	v_mfma_f32_16x16x32_bf16 v[52:55], v[204:207], v[212:215], v[52:55]
	ds_read_b128 v[146:149], v249 offset:1024
	v_mfma_f32_16x16x32_bf16 v[44:47], v[174:177], v[220:223], v[44:47]
	ds_read_b128 v[154:157], v249 offset:2048
	v_mfma_f32_16x16x32_bf16 v[36:39], v[204:207], v[220:223], v[36:39]
	ds_read_b128 v[158:161], v249 offset:3072
	v_mfma_f32_16x16x32_bf16 v[28:31], v[174:177], v[228:231], v[28:31]
	v_mfma_f32_16x16x32_bf16 v[20:23], v[204:207], v[228:231], v[20:23]
	v_mfma_f32_16x16x32_bf16 v[12:15], v[174:177], v[236:239], v[12:15]
	v_mfma_f32_16x16x32_bf16 v[4:7], v[204:207], v[236:239], v[4:7]
	v_mfma_f32_16x16x32_bf16 v[60:63], v[178:181], v[216:219], v[60:63]
	v_mfma_f32_16x16x32_bf16 v[52:55], v[208:211], v[216:219], v[52:55]
	v_mfma_f32_16x16x32_bf16 v[44:47], v[178:181], v[224:227], v[44:47]
	v_mfma_f32_16x16x32_bf16 v[36:39], v[208:211], v[224:227], v[36:39]
	v_mfma_f32_16x16x32_bf16 v[28:31], v[178:181], v[232:235], v[28:31]
	v_mfma_f32_16x16x32_bf16 v[20:23], v[208:211], v[232:235], v[20:23]
	v_mfma_f32_16x16x32_bf16 v[12:15], v[178:181], v[240:243], v[12:15]
	v_mfma_f32_16x16x32_bf16 v[4:7], v[208:211], v[240:243], v[4:7]
	s_add_i32 s60, s60, 2
	s_add_u32 s36, s36, 0x100
	s_addc_u32 s37, s37, 0
	s_add_u32 s58, s58, 0x100
	s_addc_u32 s59, s59, 0
	s_add_u32 s38, s36, 0xfff80080
	s_addc_u32 s39, s37, -1
	s_add_i32 s61, 0, 0x10000
	s_cmp_eq_u32 s60, 28
	s_cselect_b32 s41, s11, s39
	s_cselect_b32 s40, s13, s38
	s_cselect_b32 s39, s56, s59
	s_cselect_b32 s38, s57, s58
	s_add_i32 s64, 0, 0x14000
	s_setprio 3
	s_barrier
	s_cmp_gt_u32 s60, 29
	s_cbranch_scc0 .LBB0_301
	s_and_b64 vcc, exec, s[8:9]
	s_cbranch_vccz .LBB0_304
	s_barrier

; #define PG8_STAGE(bufoff, gbase, voff) do { _Pragma("unroll") for (int _i = 0; _i < 2; ++_i) \
;         __builtin_amdgcn_global_load_lds((const unsigned*)((const char*)(gbase) + (voff)[_i]), (PG8_LAS unsigned*)(lds + (bufoff) + ldsw + _i * 8192), 16, 0, 0); } while (0)
; #define PG8_LDA(dst, b, h) do { _Pragma("unroll") for (int m = 0; m < 4; ++m) _Pragma("unroll") for (int k = 0; k < 2; ++k) dst[m][k] = *(const PG8_LAS bf16x8*)(lds + PG8_SA(b, h) + aoff + m * 2048 + k * 1024); } while (0)
; #define PG8_LDB(dst, b, h) do { _Pragma("unroll") for (int n = 0; n < 2; ++n) _Pragma("unroll") for (int k = 0; k < 2; ++k) dst[n][k] = *(const PG8_LAS bf16x8*)(lds + PG8_SB(b, h) + boff + n * 2048 + k * 1024); } while (0)
; #define PG8_MMA(ai, bj, At, Bt) do { __builtin_amdgcn_s_setprio(1); _Pragma("unroll") for (int m = 0; m < 4; ++m) _Pragma("unroll") for (int n = 0; n < 2; ++n) _Pragma("unroll") for (int k = 0; k < 2; ++k) \
;         acc[ai][bj][m][n] = __builtin_amdgcn_mfma_f32_16x16x32_bf16(Bt[n][k], At[m][k], acc[ai][bj][m][n], 0, 0, 0); __builtin_amdgcn_s_setprio(0); } while (0)
; #define PG8_WAIT_V(n) asm volatile("s_waitcnt vmcnt(" #n ")" ::: "memory")
; #define PG8_WAIT_L(n) asm volatile("s_waitcnt lgkmcnt(" #n ")" ::: "memory")
; #define PG8_BAR __builtin_amdgcn_s_barrier()
; #define PG8_SCHED __builtin_amdgcn_sched_barrier(0)
; template <class Epi, class Sched, bool ALIGN_EPI = false, bool SP2 = false>
; __device__ __forceinline__ void gemm_phase(PG8_LAS unsigned char* lds, const Gemm g, const Sched& S, const Epi& E) {
;     ...
;             PG8_LDB(B0, 0, 0); PG8_LDB(B1, 0, 1); PG8_SCHED; PG8_LDA(At, 0, 0); PG8_STAGE(PG8_SA(1, 1), a1 + hstep, voffA);
;             PG8_WAIT_V(8); PG8_WAIT_L(0); PG8_BAR; PG8_MMA(0, 0, At, B0); PG8_MMA(0, 1, At, B1); PG8_BAR; PG8_SCHED;
;             PG8_LDA(At, 0, 1); PG8_STAGE(PG8_SB(0, 0), b2, voffB); PG8_STAGE(PG8_SB(0, 1), b2 + hstep, voffB); PG8_STAGE(PG8_SA(0, 0), a2, voffA);
;             PG8_WAIT_V(8); PG8_WAIT_L(0); PG8_BAR; PG8_MMA(1, 0, At, B0); PG8_MMA(1, 1, At, B1); PG8_BAR; PG8_SCHED;
.LBB0_575:
	ds_read_b128 v[158:161], v247 offset:16384
	ds_read_b128 v[174:177], v247 offset:17408
	ds_read_b128 v[180:183], v247 offset:18432
	ds_read_b128 v[204:207], v247 offset:19456
	v_lshl_add_u64 v[162:163], s[34:35], 0, v[138:139]
	s_add_i32 m0, s47, 0xc000
	ds_read_b128 v[208:211], v179
	ds_read_b128 v[212:215], v179 offset:1024
	ds_read_b128 v[216:219], v179 offset:2048
	ds_read_b128 v[220:223], v179 offset:3072
	ds_read_b128 v[224:227], v179 offset:4096
	ds_read_b128 v[228:231], v179 offset:5120
	ds_read_b128 v[232:235], v179 offset:6144
	ds_read_b128 v[236:239], v179 offset:7168
	global_load_lds_dwordx4 v[162:163], off
	v_lshl_add_u64 v[162:163], s[34:35], 0, v[140:141]
	s_add_i32 m0, s47, 0xe000
	s_nop 0
	global_load_lds_dwordx4 v[162:163], off
	s_waitcnt vmcnt(8) lgkmcnt(0)
	s_setprio 0
	s_barrier
	v_mfma_f32_16x16x32_bf16 v[128:131], v[142:145], v[208:211], v[128:131]
	v_mfma_f32_16x16x32_bf16 v[124:127], v[150:153], v[208:211], v[124:127]
	v_mfma_f32_16x16x32_bf16 v[112:115], v[142:145], v[216:219], v[112:115]
	v_mfma_f32_16x16x32_bf16 v[108:111], v[150:153], v[216:219], v[108:111]
	v_mfma_f32_16x16x32_bf16 v[96:99], v[142:145], v[224:227], v[96:99]
	v_mfma_f32_16x16x32_bf16 v[92:95], v[150:153], v[224:227], v[92:95]
	v_mfma_f32_16x16x32_bf16 v[80:83], v[142:145], v[232:235], v[80:83]
	v_mfma_f32_16x16x32_bf16 v[76:79], v[150:153], v[232:235], v[76:79]
	v_mfma_f32_16x16x32_bf16 v[128:131], v[146:149], v[212:215], v[128:131]
	v_mfma_f32_16x16x32_bf16 v[124:127], v[154:157], v[212:215], v[124:127]
	v_mfma_f32_16x16x32_bf16 v[112:115], v[146:149], v[220:223], v[112:115]
	v_mfma_f32_16x16x32_bf16 v[108:111], v[154:157], v[220:223], v[108:111]
	v_mfma_f32_16x16x32_bf16 v[96:99], v[146:149], v[228:231], v[96:99]
	v_mfma_f32_16x16x32_bf16 v[92:95], v[154:157], v[228:231], v[92:95]
	v_mfma_f32_16x16x32_bf16 v[80:83], v[146:149], v[236:239], v[80:83]
	v_mfma_f32_16x16x32_bf16 v[76:79], v[154:157], v[236:239], v[76:79]
	v_mfma_f32_16x16x32_bf16 v[120:123], v[158:161], v[208:211], v[120:123]
	v_mfma_f32_16x16x32_bf16 v[116:119], v[180:183], v[208:211], v[116:119]
	v_mfma_f32_16x16x32_bf16 v[104:107], v[158:161], v[216:219], v[104:107]
	v_mfma_f32_16x16x32_bf16 v[100:103], v[180:183], v[216:219], v[100:103]
	v_mfma_f32_16x16x32_bf16 v[88:91], v[158:161], v[224:227], v[88:91]
	v_mfma_f32_16x16x32_bf16 v[84:87], v[180:183], v[224:227], v[84:87]
	v_mfma_f32_16x16x32_bf16 v[72:75], v[158:161], v[232:235], v[72:75]
	v_mfma_f32_16x16x32_bf16 v[68:71], v[180:183], v[232:235], v[68:71]
	v_mfma_f32_16x16x32_bf16 v[120:123], v[174:177], v[212:215], v[120:123]
	v_mfma_f32_16x16x32_bf16 v[116:119], v[204:207], v[212:215], v[116:119]
	v_mfma_f32_16x16x32_bf16 v[104:107], v[174:177], v[220:223], v[104:107]
	v_mfma_f32_16x16x32_bf16 v[100:103], v[204:207], v[220:223], v[100:103]
	v_mfma_f32_16x16x32_bf16 v[88:91], v[174:177], v[228:231], v[88:91]
	v_mfma_f32_16x16x32_bf16 v[84:87], v[204:207], v[228:231], v[84:87]
	v_mfma_f32_16x16x32_bf16 v[72:75], v[174:177], v[236:239], v[72:75]
	v_mfma_f32_16x16x32_bf16 v[68:71], v[204:207], v[236:239], v[68:71]
	s_setprio 3
	s_barrier
	s_add_i32 s34, s64, s46
	s_mov_b32 m0, s34
	ds_read_b128 v[208:211], v179 offset:16384
	ds_read_b128 v[212:215], v179 offset:17408
	ds_read_b128 v[216:219], v179 offset:18432
	ds_read_b128 v[220:223], v179 offset:19456
	ds_read_b128 v[224:227], v179 offset:20480
	ds_read_b128 v[228:231], v179 offset:21504
	ds_read_b128 v[232:235], v179 offset:22528
	ds_read_b128 v[236:239], v179 offset:23552
	global_load_lds_dwordx4 v2, s[38:39]
	s_add_i32 m0, s34, 0x2000
	s_add_u32 s34, s38, 0x158000
	s_addc_u32 s35, s39, 0
	s_add_i32 s64, s65, s46
	global_load_lds_dwordx4 v132, s[38:39]
	s_mov_b32 m0, s64
	s_nop 0
	global_load_lds_dwordx4 v2, s[34:35]
	s_add_i32 m0, s64, 0x2000
	s_nop 0
	global_load_lds_dwordx4 v132, s[34:35]
	s_mov_b32 m0, s47
	s_nop 0
	global_load_lds_dwordx4 v2, s[40:41]
	s_mov_b32 m0, s48
	s_nop 0
	global_load_lds_dwordx4 v132, s[40:41]
	s_waitcnt vmcnt(8) lgkmcnt(0)
	s_setprio 0
	s_barrier
	v_mfma_f32_16x16x32_bf16 v[64:67], v[142:145], v[208:211], v[64:67]
	v_mfma_f32_16x16x32_bf16 v[60:63], v[150:153], v[208:211], v[60:63]
	v_mfma_f32_16x16x32_bf16 v[48:51], v[142:145], v[216:219], v[48:51]
	v_mfma_f32_16x16x32_bf16 v[44:47], v[150:153], v[216:219], v[44:47]
	v_mfma_f32_16x16x32_bf16 v[32:35], v[142:145], v[224:227], v[32:35]
	v_mfma_f32_16x16x32_bf16 v[28:31], v[150:153], v[224:227], v[28:31]
	v_mfma_f32_16x16x32_bf16 v[16:19], v[142:145], v[232:235], v[16:19]
	v_mfma_f32_16x16x32_bf16 v[12:15], v[150:153], v[232:235], v[12:15]
	v_mfma_f32_16x16x32_bf16 v[64:67], v[146:149], v[212:215], v[64:67]
	v_mfma_f32_16x16x32_bf16 v[60:63], v[154:157], v[212:215], v[60:63]
	v_mfma_f32_16x16x32_bf16 v[48:51], v[146:149], v[220:223], v[48:51]
	v_mfma_f32_16x16x32_bf16 v[44:47], v[154:157], v[220:223], v[44:47]
	v_mfma_f32_16x16x32_bf16 v[32:35], v[146:149], v[228:231], v[32:35]
	v_mfma_f32_16x16x32_bf16 v[28:31], v[154:157], v[228:231], v[28:31]
	v_mfma_f32_16x16x32_bf16 v[16:19], v[146:149], v[236:239], v[16:19]
	v_mfma_f32_16x16x32_bf16 v[12:15], v[154:157], v[236:239], v[12:15]
	v_mfma_f32_16x16x32_bf16 v[56:59], v[158:161], v[208:211], v[56:59]
	ds_read_b128 v[142:145], v247 offset:32768
	v_mfma_f32_16x16x32_bf16 v[52:55], v[180:183], v[208:211], v[52:55]
	ds_read_b128 v[146:149], v247 offset:33792
	v_mfma_f32_16x16x32_bf16 v[40:43], v[158:161], v[216:219], v[40:43]
	ds_read_b128 v[150:153], v247 offset:34816
	v_mfma_f32_16x16x32_bf16 v[36:39], v[180:183], v[216:219], v[36:39]
	ds_read_b128 v[154:157], v247 offset:35840
	v_mfma_f32_16x16x32_bf16 v[24:27], v[158:161], v[224:227], v[24:27]
	v_mfma_f32_16x16x32_bf16 v[20:23], v[180:183], v[224:227], v[20:23]
	v_mfma_f32_16x16x32_bf16 v[8:11], v[158:161], v[232:235], v[8:11]
	v_mfma_f32_16x16x32_bf16 v[4:7], v[180:183], v[232:235], v[4:7]
	v_mfma_f32_16x16x32_bf16 v[56:59], v[174:177], v[212:215], v[56:59]
	v_mfma_f32_16x16x32_bf16 v[52:55], v[204:207], v[212:215], v[52:55]
	v_mfma_f32_16x16x32_bf16 v[40:43], v[174:177], v[220:223], v[40:43]
	v_mfma_f32_16x16x32_bf16 v[36:39], v[204:207], v[220:223], v[36:39]
	v_mfma_f32_16x16x32_bf16 v[24:27], v[174:177], v[228:231], v[24:27]
	v_mfma_f32_16x16x32_bf16 v[20:23], v[204:207], v[228:231], v[20:23]
	v_mfma_f32_16x16x32_bf16 v[8:11], v[174:177], v[236:239], v[8:11]
	v_mfma_f32_16x16x32_bf16 v[4:7], v[204:207], v[236:239], v[4:7]
	s_setprio 3
	s_barrier
; #define PG8_STAGE(bufoff, gbase, voff) do { _Pragma("unroll") for (int _i = 0; _i < 2; ++_i) \
;         __builtin_amdgcn_global_load_lds((const unsigned*)((const char*)(gbase) + (voff)[_i]), (PG8_LAS unsigned*)(lds + (bufoff) + ldsw + _i * 8192), 16, 0, 0); } while (0)
; #define PG8_LDA(dst, b, h) do { _Pragma("unroll") for (int m = 0; m < 4; ++m) _Pragma("unroll") for (int k = 0; k < 2; ++k) dst[m][k] = *(const PG8_LAS bf16x8*)(lds + PG8_SA(b, h) + aoff + m * 2048 + k * 1024); } while (0)
; #define PG8_LDB(dst, b, h) do { _Pragma("unroll") for (int n = 0; n < 2; ++n) _Pragma("unroll") for (int k = 0; k < 2; ++k) dst[n][k] = *(const PG8_LAS bf16x8*)(lds + PG8_SB(b, h) + boff + n * 2048 + k * 1024); } while (0)
; #define PG8_MMA(ai, bj, At, Bt) do { __builtin_amdgcn_s_setprio(1); _Pragma("unroll") for (int m = 0; m < 4; ++m) _Pragma("unroll") for (int n = 0; n < 2; ++n) _Pragma("unroll") for (int k = 0; k < 2; ++k) \
;         acc[ai][bj][m][n] = __builtin_amdgcn_mfma_f32_16x16x32_bf16(Bt[n][k], At[m][k], acc[ai][bj][m][n], 0, 0, 0); __builtin_amdgcn_s_setprio(0); } while (0)
; #define PG8_WAIT_V(n) asm volatile("s_waitcnt vmcnt(" #n ")" ::: "memory")
; #define PG8_WAIT_L(n) asm volatile("s_waitcnt lgkmcnt(" #n ")" ::: "memory")
; template <class Epi, class Sched, bool ALIGN_EPI = false, bool SP2 = false>
; __device__ __forceinline__ void gemm_phase(PG8_LAS unsigned char* lds, const Gemm g, const Sched& S, const Epi& E) {
;     ...
;         for (int t = 0; t < nt; t += 2) {
;             const bool last = (t == nt - 2);
;             const char* a1 = cA + (size_t)(t + 1) * kstep;
;             const char* a2 = last ? nA : cA + (size_t)(t + 2) * kstep; const char* b2 = last ? nB : cB + (size_t)(t + 2) * kstep;
;             const char* a3 = a2 + kstep; const char* b3 = b2 + kstep;
;             if (last && has_next) S.a_ready(nxt);
;     ...
;             PG8_LDB(B0, 1, 0); PG8_LDB(B1, 1, 1); PG8_SCHED; PG8_LDA(At, 1, 0); PG8_STAGE(PG8_SA(0, 1), a2 + hstep, voffA);
;             PG8_WAIT_V(8); PG8_WAIT_L(0); PG8_BAR; PG8_MMA(0, 0, At, B0); PG8_MMA(0, 1, At, B1); PG8_BAR; PG8_SCHED;
;             PG8_LDA(At, 1, 1); PG8_STAGE(PG8_SB(1, 0), b3, voffB); PG8_STAGE(PG8_SB(1, 1), b3 + hstep, voffB); PG8_STAGE(PG8_SA(1, 0), a3, voffA);
;             PG8_WAIT_V(8); PG8_WAIT_L(0); PG8_BAR; PG8_MMA(1, 0, At, B0); PG8_MMA(1, 1, At, B1); PG8_BAR; PG8_SCHED;
	s_add_i32 s64, 0, 0x18000
	s_add_i32 s65, 0, 0x1c000
	ds_read_b128 v[158:161], v247 offset:49152
	ds_read_b128 v[174:177], v247 offset:50176
	ds_read_b128 v[180:183], v247 offset:51200
	ds_read_b128 v[204:207], v247 offset:52224
	s_add_u32 s34, s40, 0x158000
	s_addc_u32 s35, s41, 0
	s_mov_b32 m0, s49
	ds_read_b128 v[208:211], v179 offset:32768
	ds_read_b128 v[212:215], v179 offset:33792
	ds_read_b128 v[216:219], v179 offset:34816
	ds_read_b128 v[220:223], v179 offset:35840
	ds_read_b128 v[224:227], v179 offset:36864
	ds_read_b128 v[228:231], v179 offset:37888
	ds_read_b128 v[232:235], v179 offset:38912
	ds_read_b128 v[236:239], v179 offset:39936
	global_load_lds_dwordx4 v2, s[34:35]
	s_mov_b32 m0, s50
	s_nop 0
	global_load_lds_dwordx4 v132, s[34:35]
	s_nop 0
	s_waitcnt vmcnt(8) lgkmcnt(0)
	s_setprio 0
	s_barrier
	v_mfma_f32_16x16x32_bf16 v[128:131], v[142:145], v[208:211], v[128:131]
	v_mfma_f32_16x16x32_bf16 v[124:127], v[150:153], v[208:211], v[124:127]
	v_mfma_f32_16x16x32_bf16 v[112:115], v[142:145], v[216:219], v[112:115]
	v_mfma_f32_16x16x32_bf16 v[108:111], v[150:153], v[216:219], v[108:111]
	v_mfma_f32_16x16x32_bf16 v[96:99], v[142:145], v[224:227], v[96:99]
	v_mfma_f32_16x16x32_bf16 v[92:95], v[150:153], v[224:227], v[92:95]
	v_mfma_f32_16x16x32_bf16 v[80:83], v[142:145], v[232:235], v[80:83]
	v_mfma_f32_16x16x32_bf16 v[76:79], v[150:153], v[232:235], v[76:79]
	v_mfma_f32_16x16x32_bf16 v[128:131], v[146:149], v[212:215], v[128:131]
	v_mfma_f32_16x16x32_bf16 v[124:127], v[154:157], v[212:215], v[124:127]
	v_mfma_f32_16x16x32_bf16 v[112:115], v[146:149], v[220:223], v[112:115]
	v_mfma_f32_16x16x32_bf16 v[108:111], v[154:157], v[220:223], v[108:111]
	v_mfma_f32_16x16x32_bf16 v[96:99], v[146:149], v[228:231], v[96:99]
	v_mfma_f32_16x16x32_bf16 v[92:95], v[154:157], v[228:231], v[92:95]
	v_mfma_f32_16x16x32_bf16 v[80:83], v[146:149], v[236:239], v[80:83]
	v_mfma_f32_16x16x32_bf16 v[76:79], v[154:157], v[236:239], v[76:79]
	v_mfma_f32_16x16x32_bf16 v[120:123], v[158:161], v[208:211], v[120:123]
	v_mfma_f32_16x16x32_bf16 v[116:119], v[180:183], v[208:211], v[116:119]
	v_mfma_f32_16x16x32_bf16 v[104:107], v[158:161], v[216:219], v[104:107]
	v_mfma_f32_16x16x32_bf16 v[100:103], v[180:183], v[216:219], v[100:103]
	v_mfma_f32_16x16x32_bf16 v[88:91], v[158:161], v[224:227], v[88:91]
	v_mfma_f32_16x16x32_bf16 v[84:87], v[180:183], v[224:227], v[84:87]
	v_mfma_f32_16x16x32_bf16 v[72:75], v[158:161], v[232:235], v[72:75]
	v_mfma_f32_16x16x32_bf16 v[68:71], v[180:183], v[232:235], v[68:71]
	v_mfma_f32_16x16x32_bf16 v[120:123], v[174:177], v[212:215], v[120:123]
	v_mfma_f32_16x16x32_bf16 v[116:119], v[204:207], v[212:215], v[116:119]
	v_mfma_f32_16x16x32_bf16 v[104:107], v[174:177], v[220:223], v[104:107]
	v_mfma_f32_16x16x32_bf16 v[100:103], v[204:207], v[220:223], v[100:103]
	v_mfma_f32_16x16x32_bf16 v[88:91], v[174:177], v[228:231], v[88:91]
	v_mfma_f32_16x16x32_bf16 v[84:87], v[204:207], v[228:231], v[84:87]
	v_mfma_f32_16x16x32_bf16 v[72:75], v[174:177], v[236:239], v[72:75]
	v_mfma_f32_16x16x32_bf16 v[68:71], v[204:207], v[236:239], v[68:71]
	s_setprio 3
	s_barrier
	s_add_i32 s34, s64, s46
	s_add_i32 m0, s34, 0xffffff80
	ds_read_b128 v[208:211], v179 offset:49152
	ds_read_b128 v[212:215], v179 offset:50176
	ds_read_b128 v[216:219], v179 offset:51200
	ds_read_b128 v[220:223], v179 offset:52224
	ds_read_b128 v[224:227], v179 offset:53248
	ds_read_b128 v[228:231], v179 offset:54272
	ds_read_b128 v[232:235], v179 offset:55296
	ds_read_b128 v[236:239], v179 offset:56320
	global_load_lds_dwordx4 v2, s[38:39] offset:128
	s_add_i32 m0, s34, 0x1f80
	s_add_u32 s34, s38, 0x158080
	s_addc_u32 s35, s39, 0
	global_load_lds_dwordx4 v132, s[38:39] offset:128
	s_add_i32 s38, s65, s46
	s_mov_b32 m0, s38
	s_nop 0
	global_load_lds_dwordx4 v2, s[34:35]
	s_add_i32 m0, s38, 0x2000
	s_nop 0
	global_load_lds_dwordx4 v132, s[34:35]
	s_add_i32 m0, s53, 0xffffff80
	s_nop 0
	global_load_lds_dwordx4 v2, s[40:41] offset:128
	s_add_i32 m0, s54, 0xffffff80
	s_nop 0
	global_load_lds_dwordx4 v132, s[40:41] offset:128
	s_nop 0
	s_waitcnt vmcnt(8) lgkmcnt(0)
	s_setprio 0
	s_barrier
	v_mfma_f32_16x16x32_bf16 v[64:67], v[142:145], v[208:211], v[64:67]
	v_mfma_f32_16x16x32_bf16 v[60:63], v[150:153], v[208:211], v[60:63]
	v_mfma_f32_16x16x32_bf16 v[48:51], v[142:145], v[216:219], v[48:51]
	v_mfma_f32_16x16x32_bf16 v[44:47], v[150:153], v[216:219], v[44:47]
	v_mfma_f32_16x16x32_bf16 v[32:35], v[142:145], v[224:227], v[32:35]
	v_mfma_f32_16x16x32_bf16 v[28:31], v[150:153], v[224:227], v[28:31]
	v_mfma_f32_16x16x32_bf16 v[16:19], v[142:145], v[232:235], v[16:19]
	v_mfma_f32_16x16x32_bf16 v[12:15], v[150:153], v[232:235], v[12:15]
	v_mfma_f32_16x16x32_bf16 v[64:67], v[146:149], v[212:215], v[64:67]
	v_mfma_f32_16x16x32_bf16 v[60:63], v[154:157], v[212:215], v[60:63]
	v_mfma_f32_16x16x32_bf16 v[48:51], v[146:149], v[220:223], v[48:51]
	v_mfma_f32_16x16x32_bf16 v[44:47], v[154:157], v[220:223], v[44:47]
	v_mfma_f32_16x16x32_bf16 v[32:35], v[146:149], v[228:231], v[32:35]
	v_mfma_f32_16x16x32_bf16 v[28:31], v[154:157], v[228:231], v[28:31]
	v_mfma_f32_16x16x32_bf16 v[16:19], v[146:149], v[236:239], v[16:19]
	v_mfma_f32_16x16x32_bf16 v[12:15], v[154:157], v[236:239], v[12:15]
	v_mfma_f32_16x16x32_bf16 v[56:59], v[158:161], v[208:211], v[56:59]
	ds_read_b128 v[142:145], v247
	v_mfma_f32_16x16x32_bf16 v[52:55], v[180:183], v[208:211], v[52:55]
	ds_read_b128 v[146:149], v247 offset:1024
	v_mfma_f32_16x16x32_bf16 v[40:43], v[158:161], v[216:219], v[40:43]
	ds_read_b128 v[150:153], v247 offset:2048
	v_mfma_f32_16x16x32_bf16 v[36:39], v[180:183], v[216:219], v[36:39]
	ds_read_b128 v[154:157], v247 offset:3072
	v_mfma_f32_16x16x32_bf16 v[24:27], v[158:161], v[224:227], v[24:27]
	v_mfma_f32_16x16x32_bf16 v[20:23], v[180:183], v[224:227], v[20:23]
	v_mfma_f32_16x16x32_bf16 v[8:11], v[158:161], v[232:235], v[8:11]
	v_mfma_f32_16x16x32_bf16 v[4:7], v[180:183], v[232:235], v[4:7]
	v_mfma_f32_16x16x32_bf16 v[56:59], v[174:177], v[212:215], v[56:59]
	v_mfma_f32_16x16x32_bf16 v[52:55], v[204:207], v[212:215], v[52:55]
	v_mfma_f32_16x16x32_bf16 v[40:43], v[174:177], v[220:223], v[40:43]
	v_mfma_f32_16x16x32_bf16 v[36:39], v[204:207], v[220:223], v[36:39]
	v_mfma_f32_16x16x32_bf16 v[24:27], v[174:177], v[228:231], v[24:27]
	v_mfma_f32_16x16x32_bf16 v[20:23], v[204:207], v[228:231], v[20:23]
	v_mfma_f32_16x16x32_bf16 v[8:11], v[174:177], v[236:239], v[8:11]
	v_mfma_f32_16x16x32_bf16 v[4:7], v[204:207], v[236:239], v[4:7]
	s_add_i32 s63, s63, 2
	s_add_u32 s61, s61, 0x100
	s_addc_u32 s62, s62, 0
	s_mov_b64 s[34:35], s[36:37]
	s_add_u32 s36, s34, 0x100
	s_addc_u32 s37, s35, 0
	s_add_i32 s64, 0, 0x10000
	s_cmpk_eq_i32 s63, 0x52
	s_cselect_b32 s41, s5, s37
	s_cselect_b32 s40, s4, s36
	s_cselect_b32 s39, s31, s62
	s_cselect_b32 s38, s30, s61
	s_add_i32 s65, 0, 0x14000
	s_setprio 3
	s_barrier
	s_cmpk_gt_u32 s63, 0x53
	s_cbranch_scc0 .LBB0_575
	s_and_b64 vcc, exec, s[28:29]
	s_cbranch_vccz .LBB0_578
	s_barrier

; #define PG8_STAGE(bufoff, gbase, voff) do { _Pragma("unroll") for (int _i = 0; _i < 2; ++_i) \
;         __builtin_amdgcn_global_load_lds((const unsigned*)((const char*)(gbase) + (voff)[_i]), (PG8_LAS unsigned*)(lds + (bufoff) + ldsw + _i * 8192), 16, 0, 0); } while (0)
; #define PG8_LDA(dst, b, h) do { _Pragma("unroll") for (int m = 0; m < 4; ++m) _Pragma("unroll") for (int k = 0; k < 2; ++k) dst[m][k] = *(const PG8_LAS bf16x8*)(lds + PG8_SA(b, h) + aoff + m * 2048 + k * 1024); } while (0)
; #define PG8_LDB(dst, b, h) do { _Pragma("unroll") for (int n = 0; n < 2; ++n) _Pragma("unroll") for (int k = 0; k < 2; ++k) dst[n][k] = *(const PG8_LAS bf16x8*)(lds + PG8_SB(b, h) + boff + n * 2048 + k * 1024); } while (0)
; #define PG8_MMA(ai, bj, At, Bt) do { __builtin_amdgcn_s_setprio(1); _Pragma("unroll") for (int m = 0; m < 4; ++m) _Pragma("unroll") for (int n = 0; n < 2; ++n) _Pragma("unroll") for (int k = 0; k < 2; ++k) \
;         acc[ai][bj][m][n] = __builtin_amdgcn_mfma_f32_16x16x32_bf16(Bt[n][k], At[m][k], acc[ai][bj][m][n], 0, 0, 0); __builtin_amdgcn_s_setprio(0); } while (0)
; #define PG8_WAIT_V(n) asm volatile("s_waitcnt vmcnt(" #n ")" ::: "memory")
; #define PG8_WAIT_L(n) asm volatile("s_waitcnt lgkmcnt(" #n ")" ::: "memory")
; #define PG8_BAR __builtin_amdgcn_s_barrier()
; #define PG8_SCHED __builtin_amdgcn_sched_barrier(0)
; template <class Epi, class Sched, bool ALIGN_EPI = false, bool SP2 = false>
; __device__ __forceinline__ void gemm_phase(PG8_LAS unsigned char* lds, const Gemm g, const Sched& S, const Epi& E) {
;     ...
;             PG8_LDB(B0, 0, 0); PG8_LDB(B1, 0, 1); PG8_SCHED; PG8_LDA(At, 0, 0); PG8_STAGE(PG8_SA(1, 1), a1 + hstep, voffA);
;             PG8_WAIT_V(8); PG8_WAIT_L(0); PG8_BAR; PG8_MMA(0, 0, At, B0); PG8_MMA(0, 1, At, B1); PG8_BAR; PG8_SCHED;
;             PG8_LDA(At, 0, 1); PG8_STAGE(PG8_SB(0, 0), b2, voffB); PG8_STAGE(PG8_SB(0, 1), b2 + hstep, voffB); PG8_STAGE(PG8_SA(0, 0), a2, voffA);
;             PG8_WAIT_V(8); PG8_WAIT_L(0); PG8_BAR; PG8_MMA(1, 0, At, B0); PG8_MMA(1, 1, At, B1); PG8_BAR; PG8_SCHED;
.LBB0_674:
	ds_read_b128 v[158:161], v249 offset:16384
	ds_read_b128 v[174:177], v249 offset:17408
	ds_read_b128 v[206:209], v249 offset:18432
	ds_read_b128 v[210:213], v249 offset:19456
	s_add_i32 m0, s39, 0xc000
	ds_read_b128 v[214:217], v204
	ds_read_b128 v[218:221], v204 offset:1024
	ds_read_b128 v[222:225], v204 offset:2048
	ds_read_b128 v[226:229], v204 offset:3072
	ds_read_b128 v[230:233], v204 offset:4096
	ds_read_b128 v[234:237], v204 offset:5120
	ds_read_b128 v[238:241], v204 offset:6144
	ds_read_b128 v[242:245], v204 offset:7168
	global_load_lds_dwordx4 v154, s[40:41]
	s_add_i32 m0, s39, 0xe000
	s_nop 0
	global_load_lds_dwordx4 v156, s[40:41]
	s_waitcnt vmcnt(8) lgkmcnt(0)
	s_setprio 0
	s_barrier
	v_mfma_f32_16x16x32_bf16 v[128:131], v[132:135], v[214:217], v[128:131]
	v_mfma_f32_16x16x32_bf16 v[124:127], v[140:143], v[214:217], v[124:127]
	v_mfma_f32_16x16x32_bf16 v[116:119], v[132:135], v[222:225], v[116:119]
	v_mfma_f32_16x16x32_bf16 v[108:111], v[140:143], v[222:225], v[108:111]
	v_mfma_f32_16x16x32_bf16 v[100:103], v[132:135], v[230:233], v[100:103]
	v_mfma_f32_16x16x32_bf16 v[92:95], v[140:143], v[230:233], v[92:95]
	v_mfma_f32_16x16x32_bf16 v[84:87], v[132:135], v[238:241], v[84:87]
	v_mfma_f32_16x16x32_bf16 v[76:79], v[140:143], v[238:241], v[76:79]
	v_mfma_f32_16x16x32_bf16 v[128:131], v[136:139], v[218:221], v[128:131]
	v_mfma_f32_16x16x32_bf16 v[124:127], v[144:147], v[218:221], v[124:127]
	v_mfma_f32_16x16x32_bf16 v[116:119], v[136:139], v[226:229], v[116:119]
	v_mfma_f32_16x16x32_bf16 v[108:111], v[144:147], v[226:229], v[108:111]
	v_mfma_f32_16x16x32_bf16 v[100:103], v[136:139], v[234:237], v[100:103]
	v_mfma_f32_16x16x32_bf16 v[92:95], v[144:147], v[234:237], v[92:95]
	v_mfma_f32_16x16x32_bf16 v[84:87], v[136:139], v[242:245], v[84:87]
	v_mfma_f32_16x16x32_bf16 v[76:79], v[144:147], v[242:245], v[76:79]
	v_mfma_f32_16x16x32_bf16 v[120:123], v[158:161], v[214:217], v[120:123]
	v_mfma_f32_16x16x32_bf16 v[112:115], v[206:209], v[214:217], v[112:115]
	v_mfma_f32_16x16x32_bf16 v[104:107], v[158:161], v[222:225], v[104:107]
	v_mfma_f32_16x16x32_bf16 v[96:99], v[206:209], v[222:225], v[96:99]
	v_mfma_f32_16x16x32_bf16 v[88:91], v[158:161], v[230:233], v[88:91]
	v_mfma_f32_16x16x32_bf16 v[80:83], v[206:209], v[230:233], v[80:83]
	v_mfma_f32_16x16x32_bf16 v[72:75], v[158:161], v[238:241], v[72:75]
	v_mfma_f32_16x16x32_bf16 v[68:71], v[206:209], v[238:241], v[68:71]
	v_mfma_f32_16x16x32_bf16 v[120:123], v[174:177], v[218:221], v[120:123]
	v_mfma_f32_16x16x32_bf16 v[112:115], v[210:213], v[218:221], v[112:115]
	v_mfma_f32_16x16x32_bf16 v[104:107], v[174:177], v[226:229], v[104:107]
	v_mfma_f32_16x16x32_bf16 v[96:99], v[210:213], v[226:229], v[96:99]
	v_mfma_f32_16x16x32_bf16 v[88:91], v[174:177], v[234:237], v[88:91]
	v_mfma_f32_16x16x32_bf16 v[80:83], v[210:213], v[234:237], v[80:83]
	v_mfma_f32_16x16x32_bf16 v[72:75], v[174:177], v[242:245], v[72:75]
	v_mfma_f32_16x16x32_bf16 v[68:71], v[210:213], v[242:245], v[68:71]
	s_setprio 3
	s_barrier
	s_add_i32 s64, s64, s46
	s_mov_b32 m0, s64
	ds_read_b128 v[214:217], v204 offset:16384
	ds_read_b128 v[218:221], v204 offset:17408
	ds_read_b128 v[222:225], v204 offset:18432
	ds_read_b128 v[226:229], v204 offset:19456
	ds_read_b128 v[230:233], v204 offset:20480
	ds_read_b128 v[234:237], v204 offset:21504
	ds_read_b128 v[238:241], v204 offset:22528
	ds_read_b128 v[242:245], v204 offset:23552
	global_load_lds_dwordx4 v2, s[42:43]
	s_add_i32 m0, s64, 0x2000
	s_add_u32 s64, s42, 0x80000
	s_addc_u32 s65, s43, 0
	s_add_i32 s66, s66, s46
	global_load_lds_dwordx4 v148, s[42:43]
	s_mov_b32 m0, s66
	s_nop 0
	global_load_lds_dwordx4 v2, s[64:65]
	s_add_i32 m0, s66, 0x2000
	s_nop 0
	global_load_lds_dwordx4 v148, s[64:65]
	s_mov_b32 m0, s39
	s_nop 0
	global_load_lds_dwordx4 v152, s[44:45]
	s_mov_b32 m0, s51
	s_nop 0
	global_load_lds_dwordx4 v150, s[44:45]
	s_waitcnt vmcnt(8) lgkmcnt(0)
	s_setprio 0
	s_barrier
	v_mfma_f32_16x16x32_bf16 v[64:67], v[132:135], v[214:217], v[64:67]
	v_mfma_f32_16x16x32_bf16 v[60:63], v[140:143], v[214:217], v[60:63]
	v_mfma_f32_16x16x32_bf16 v[52:55], v[132:135], v[222:225], v[52:55]
	v_mfma_f32_16x16x32_bf16 v[44:47], v[140:143], v[222:225], v[44:47]
	v_mfma_f32_16x16x32_bf16 v[36:39], v[132:135], v[230:233], v[36:39]
	v_mfma_f32_16x16x32_bf16 v[28:31], v[140:143], v[230:233], v[28:31]
	v_mfma_f32_16x16x32_bf16 v[20:23], v[132:135], v[238:241], v[20:23]
	v_mfma_f32_16x16x32_bf16 v[12:15], v[140:143], v[238:241], v[12:15]
	v_mfma_f32_16x16x32_bf16 v[64:67], v[136:139], v[218:221], v[64:67]
	v_mfma_f32_16x16x32_bf16 v[60:63], v[144:147], v[218:221], v[60:63]
	v_mfma_f32_16x16x32_bf16 v[52:55], v[136:139], v[226:229], v[52:55]
	v_mfma_f32_16x16x32_bf16 v[44:47], v[144:147], v[226:229], v[44:47]
	v_mfma_f32_16x16x32_bf16 v[36:39], v[136:139], v[234:237], v[36:39]
	v_mfma_f32_16x16x32_bf16 v[28:31], v[144:147], v[234:237], v[28:31]
	v_mfma_f32_16x16x32_bf16 v[20:23], v[136:139], v[242:245], v[20:23]
	v_mfma_f32_16x16x32_bf16 v[12:15], v[144:147], v[242:245], v[12:15]
	v_mfma_f32_16x16x32_bf16 v[56:59], v[158:161], v[214:217], v[56:59]
	ds_read_b128 v[132:135], v249 offset:32768
	v_mfma_f32_16x16x32_bf16 v[48:51], v[206:209], v[214:217], v[48:51]
	ds_read_b128 v[136:139], v249 offset:33792
	v_mfma_f32_16x16x32_bf16 v[40:43], v[158:161], v[222:225], v[40:43]
	ds_read_b128 v[140:143], v249 offset:34816
	v_mfma_f32_16x16x32_bf16 v[32:35], v[206:209], v[222:225], v[32:35]
	ds_read_b128 v[144:147], v249 offset:35840
	v_mfma_f32_16x16x32_bf16 v[24:27], v[158:161], v[230:233], v[24:27]
	v_mfma_f32_16x16x32_bf16 v[16:19], v[206:209], v[230:233], v[16:19]
	v_mfma_f32_16x16x32_bf16 v[8:11], v[158:161], v[238:241], v[8:11]
	v_mfma_f32_16x16x32_bf16 v[4:7], v[206:209], v[238:241], v[4:7]
	v_mfma_f32_16x16x32_bf16 v[56:59], v[174:177], v[218:221], v[56:59]
	v_mfma_f32_16x16x32_bf16 v[48:51], v[210:213], v[218:221], v[48:51]
	v_mfma_f32_16x16x32_bf16 v[40:43], v[174:177], v[226:229], v[40:43]
	v_mfma_f32_16x16x32_bf16 v[32:35], v[210:213], v[226:229], v[32:35]
	v_mfma_f32_16x16x32_bf16 v[24:27], v[174:177], v[234:237], v[24:27]
	v_mfma_f32_16x16x32_bf16 v[16:19], v[210:213], v[234:237], v[16:19]
	v_mfma_f32_16x16x32_bf16 v[8:11], v[174:177], v[242:245], v[8:11]
	v_mfma_f32_16x16x32_bf16 v[4:7], v[210:213], v[242:245], v[4:7]
	s_setprio 3
	s_barrier
; #define PG8_STAGE(bufoff, gbase, voff) do { _Pragma("unroll") for (int _i = 0; _i < 2; ++_i) \
;         __builtin_amdgcn_global_load_lds((const unsigned*)((const char*)(gbase) + (voff)[_i]), (PG8_LAS unsigned*)(lds + (bufoff) + ldsw + _i * 8192), 16, 0, 0); } while (0)
; #define PG8_LDA(dst, b, h) do { _Pragma("unroll") for (int m = 0; m < 4; ++m) _Pragma("unroll") for (int k = 0; k < 2; ++k) dst[m][k] = *(const PG8_LAS bf16x8*)(lds + PG8_SA(b, h) + aoff + m * 2048 + k * 1024); } while (0)
; #define PG8_LDB(dst, b, h) do { _Pragma("unroll") for (int n = 0; n < 2; ++n) _Pragma("unroll") for (int k = 0; k < 2; ++k) dst[n][k] = *(const PG8_LAS bf16x8*)(lds + PG8_SB(b, h) + boff + n * 2048 + k * 1024); } while (0)
; #define PG8_MMA(ai, bj, At, Bt) do { __builtin_amdgcn_s_setprio(1); _Pragma("unroll") for (int m = 0; m < 4; ++m) _Pragma("unroll") for (int n = 0; n < 2; ++n) _Pragma("unroll") for (int k = 0; k < 2; ++k) \
;         acc[ai][bj][m][n] = __builtin_amdgcn_mfma_f32_16x16x32_bf16(Bt[n][k], At[m][k], acc[ai][bj][m][n], 0, 0, 0); __builtin_amdgcn_s_setprio(0); } while (0)
; #define PG8_WAIT_V(n) asm volatile("s_waitcnt vmcnt(" #n ")" ::: "memory")
; #define PG8_WAIT_L(n) asm volatile("s_waitcnt lgkmcnt(" #n ")" ::: "memory")
; template <class Epi, class Sched, bool ALIGN_EPI = false, bool SP2 = false>
; __device__ __forceinline__ void gemm_phase(PG8_LAS unsigned char* lds, const Gemm g, const Sched& S, const Epi& E) {
;     ...
;         for (int t = 0; t < nt; t += 2) {
;             const bool last = (t == nt - 2);
;             const char* a1 = cA + (size_t)(t + 1) * kstep;
;             const char* a2 = last ? nA : cA + (size_t)(t + 2) * kstep; const char* b2 = last ? nB : cB + (size_t)(t + 2) * kstep;
;             const char* a3 = a2 + kstep; const char* b3 = b2 + kstep;
;             if (last && has_next) S.a_ready(nxt);
;     ...
;             PG8_LDB(B0, 1, 0); PG8_LDB(B1, 1, 1); PG8_SCHED; PG8_LDA(At, 1, 0); PG8_STAGE(PG8_SA(0, 1), a2 + hstep, voffA);
;             PG8_WAIT_V(8); PG8_WAIT_L(0); PG8_BAR; PG8_MMA(0, 0, At, B0); PG8_MMA(0, 1, At, B1); PG8_BAR; PG8_SCHED;
;             PG8_LDA(At, 1, 1); PG8_STAGE(PG8_SB(1, 0), b3, voffB); PG8_STAGE(PG8_SB(1, 1), b3 + hstep, voffB); PG8_STAGE(PG8_SA(1, 0), a3, voffA);
;             PG8_WAIT_V(8); PG8_WAIT_L(0); PG8_BAR; PG8_MMA(1, 0, At, B0); PG8_MMA(1, 1, At, B1); PG8_BAR; PG8_SCHED;
	s_add_i32 s64, 0, 0x18000
	s_add_i32 s65, 0, 0x1c000
	ds_read_b128 v[158:161], v249 offset:49152
	ds_read_b128 v[174:177], v249 offset:50176
	ds_read_b128 v[206:209], v249 offset:51200
	ds_read_b128 v[210:213], v249 offset:52224
	s_add_u32 s100, s44, 0x80
	s_addc_u32 s101, s45, 0
	s_add_u32 s44, s44, 0x80000
	s_addc_u32 s45, s45, 0
	s_mov_b32 m0, s52
	ds_read_b128 v[214:217], v204 offset:32768
	ds_read_b128 v[218:221], v204 offset:33792
	ds_read_b128 v[222:225], v204 offset:34816
	ds_read_b128 v[226:229], v204 offset:35840
	ds_read_b128 v[230:233], v204 offset:36864
	ds_read_b128 v[234:237], v204 offset:37888
	ds_read_b128 v[238:241], v204 offset:38912
	ds_read_b128 v[242:245], v204 offset:39936
	global_load_lds_dwordx4 v152, s[44:45]
	s_mov_b32 m0, s53
	s_nop 0
	global_load_lds_dwordx4 v150, s[44:45]
	s_waitcnt vmcnt(8) lgkmcnt(0)
	s_setprio 0
	s_barrier
	v_mfma_f32_16x16x32_bf16 v[128:131], v[132:135], v[214:217], v[128:131]
	v_mfma_f32_16x16x32_bf16 v[124:127], v[140:143], v[214:217], v[124:127]
	v_mfma_f32_16x16x32_bf16 v[116:119], v[132:135], v[222:225], v[116:119]
	v_mfma_f32_16x16x32_bf16 v[108:111], v[140:143], v[222:225], v[108:111]
	v_mfma_f32_16x16x32_bf16 v[100:103], v[132:135], v[230:233], v[100:103]
	v_mfma_f32_16x16x32_bf16 v[92:95], v[140:143], v[230:233], v[92:95]
	v_mfma_f32_16x16x32_bf16 v[84:87], v[132:135], v[238:241], v[84:87]
	v_mfma_f32_16x16x32_bf16 v[76:79], v[140:143], v[238:241], v[76:79]
	v_mfma_f32_16x16x32_bf16 v[128:131], v[136:139], v[218:221], v[128:131]
	v_mfma_f32_16x16x32_bf16 v[124:127], v[144:147], v[218:221], v[124:127]
	v_mfma_f32_16x16x32_bf16 v[116:119], v[136:139], v[226:229], v[116:119]
	v_mfma_f32_16x16x32_bf16 v[108:111], v[144:147], v[226:229], v[108:111]
	v_mfma_f32_16x16x32_bf16 v[100:103], v[136:139], v[234:237], v[100:103]
	v_mfma_f32_16x16x32_bf16 v[92:95], v[144:147], v[234:237], v[92:95]
	v_mfma_f32_16x16x32_bf16 v[84:87], v[136:139], v[242:245], v[84:87]
	v_mfma_f32_16x16x32_bf16 v[76:79], v[144:147], v[242:245], v[76:79]
	v_mfma_f32_16x16x32_bf16 v[120:123], v[158:161], v[214:217], v[120:123]
	v_mfma_f32_16x16x32_bf16 v[112:115], v[206:209], v[214:217], v[112:115]
	v_mfma_f32_16x16x32_bf16 v[104:107], v[158:161], v[222:225], v[104:107]
	v_mfma_f32_16x16x32_bf16 v[96:99], v[206:209], v[222:225], v[96:99]
	v_mfma_f32_16x16x32_bf16 v[88:91], v[158:161], v[230:233], v[88:91]
	v_mfma_f32_16x16x32_bf16 v[80:83], v[206:209], v[230:233], v[80:83]
	v_mfma_f32_16x16x32_bf16 v[72:75], v[158:161], v[238:241], v[72:75]
	v_mfma_f32_16x16x32_bf16 v[68:71], v[206:209], v[238:241], v[68:71]
	v_mfma_f32_16x16x32_bf16 v[120:123], v[174:177], v[218:221], v[120:123]
	v_mfma_f32_16x16x32_bf16 v[112:115], v[210:213], v[218:221], v[112:115]
	v_mfma_f32_16x16x32_bf16 v[104:107], v[174:177], v[226:229], v[104:107]
	v_mfma_f32_16x16x32_bf16 v[96:99], v[210:213], v[226:229], v[96:99]
	v_mfma_f32_16x16x32_bf16 v[88:91], v[174:177], v[234:237], v[88:91]
	v_mfma_f32_16x16x32_bf16 v[80:83], v[210:213], v[234:237], v[80:83]
	v_mfma_f32_16x16x32_bf16 v[72:75], v[174:177], v[242:245], v[72:75]
	v_mfma_f32_16x16x32_bf16 v[68:71], v[210:213], v[242:245], v[68:71]
	s_setprio 3
	s_barrier
	s_add_i32 s44, s64, s46
	s_add_i32 m0, s44, 0xffffff80
	ds_read_b128 v[214:217], v204 offset:49152
	ds_read_b128 v[218:221], v204 offset:50176
	ds_read_b128 v[222:225], v204 offset:51200
	ds_read_b128 v[226:229], v204 offset:52224
	ds_read_b128 v[230:233], v204 offset:53248
	ds_read_b128 v[234:237], v204 offset:54272
	ds_read_b128 v[238:241], v204 offset:55296
	ds_read_b128 v[242:245], v204 offset:56320
	global_load_lds_dwordx4 v2, s[42:43] offset:128
	s_add_i32 m0, s44, 0x1f80
	s_add_i32 s44, s65, s46
	global_load_lds_dwordx4 v148, s[42:43] offset:128
	s_add_u32 s42, s42, 0x80080
	s_addc_u32 s43, s43, 0
	s_mov_b32 m0, s44
	s_nop 0
	global_load_lds_dwordx4 v2, s[42:43]
	s_add_i32 m0, s44, 0x2000
	s_nop 0
	global_load_lds_dwordx4 v148, s[42:43]
	s_mov_b32 m0, s54
	s_nop 0
	global_load_lds_dwordx4 v152, s[100:101]
	s_mov_b32 m0, s55
	s_nop 0
	global_load_lds_dwordx4 v150, s[100:101]
	s_nop 0
	s_waitcnt vmcnt(8) lgkmcnt(0)
	s_setprio 0
	s_barrier
	v_mfma_f32_16x16x32_bf16 v[64:67], v[132:135], v[214:217], v[64:67]
	v_mfma_f32_16x16x32_bf16 v[60:63], v[140:143], v[214:217], v[60:63]
	v_mfma_f32_16x16x32_bf16 v[52:55], v[132:135], v[222:225], v[52:55]
	v_mfma_f32_16x16x32_bf16 v[44:47], v[140:143], v[222:225], v[44:47]
	v_mfma_f32_16x16x32_bf16 v[36:39], v[132:135], v[230:233], v[36:39]
	v_mfma_f32_16x16x32_bf16 v[28:31], v[140:143], v[230:233], v[28:31]
	v_mfma_f32_16x16x32_bf16 v[20:23], v[132:135], v[238:241], v[20:23]
	v_mfma_f32_16x16x32_bf16 v[12:15], v[140:143], v[238:241], v[12:15]
	v_mfma_f32_16x16x32_bf16 v[64:67], v[136:139], v[218:221], v[64:67]
	v_mfma_f32_16x16x32_bf16 v[60:63], v[144:147], v[218:221], v[60:63]
	v_mfma_f32_16x16x32_bf16 v[52:55], v[136:139], v[226:229], v[52:55]
	v_mfma_f32_16x16x32_bf16 v[44:47], v[144:147], v[226:229], v[44:47]
	v_mfma_f32_16x16x32_bf16 v[36:39], v[136:139], v[234:237], v[36:39]
	v_mfma_f32_16x16x32_bf16 v[28:31], v[144:147], v[234:237], v[28:31]
	v_mfma_f32_16x16x32_bf16 v[20:23], v[136:139], v[242:245], v[20:23]
	v_mfma_f32_16x16x32_bf16 v[12:15], v[144:147], v[242:245], v[12:15]
	v_mfma_f32_16x16x32_bf16 v[56:59], v[158:161], v[214:217], v[56:59]
	ds_read_b128 v[132:135], v249
	v_mfma_f32_16x16x32_bf16 v[48:51], v[206:209], v[214:217], v[48:51]
	ds_read_b128 v[136:139], v249 offset:1024
	v_mfma_f32_16x16x32_bf16 v[40:43], v[158:161], v[222:225], v[40:43]
	ds_read_b128 v[140:143], v249 offset:2048
	v_mfma_f32_16x16x32_bf16 v[32:35], v[206:209], v[222:225], v[32:35]
	ds_read_b128 v[144:147], v249 offset:3072
	v_mfma_f32_16x16x32_bf16 v[24:27], v[158:161], v[230:233], v[24:27]
	v_mfma_f32_16x16x32_bf16 v[16:19], v[206:209], v[230:233], v[16:19]
	v_mfma_f32_16x16x32_bf16 v[8:11], v[158:161], v[238:241], v[8:11]
	v_mfma_f32_16x16x32_bf16 v[4:7], v[206:209], v[238:241], v[4:7]
	v_mfma_f32_16x16x32_bf16 v[56:59], v[174:177], v[218:221], v[56:59]
	v_mfma_f32_16x16x32_bf16 v[48:51], v[210:213], v[218:221], v[48:51]
	v_mfma_f32_16x16x32_bf16 v[40:43], v[174:177], v[226:229], v[40:43]
	v_mfma_f32_16x16x32_bf16 v[32:35], v[210:213], v[226:229], v[32:35]
	v_mfma_f32_16x16x32_bf16 v[24:27], v[174:177], v[234:237], v[24:27]
	v_mfma_f32_16x16x32_bf16 v[16:19], v[210:213], v[234:237], v[16:19]
	v_mfma_f32_16x16x32_bf16 v[8:11], v[174:177], v[242:245], v[8:11]
	v_mfma_f32_16x16x32_bf16 v[4:7], v[210:213], v[242:245], v[4:7]
	s_add_i32 s63, s63, 2
	s_add_u32 s40, s40, 0x100
	s_addc_u32 s41, s41, 0
	s_add_u32 s35, s35, 0x100
	s_addc_u32 s62, s62, 0
	s_add_u32 s42, s40, 0xfff80080
	s_addc_u32 s43, s41, -1
	s_add_i32 s64, 0, 0x10000
	s_cmp_eq_u32 s63, 28
	s_cselect_b32 s45, s5, s43
	s_cselect_b32 s44, s4, s42
	s_cselect_b32 s43, s37, s62
	s_cselect_b32 s42, s36, s35
	s_add_i32 s66, 0, 0x14000
	s_setprio 3
	s_barrier
	s_cmp_gt_u32 s63, 29
	s_cbranch_scc0 .LBB0_674
	s_and_b64 vcc, exec, s[30:31]
	s_cbranch_vccz .LBB0_677
	s_barrier

; #define PG8_STAGE(bufoff, gbase, voff) do { _Pragma("unroll") for (int _i = 0; _i < 2; ++_i) \
;         __builtin_amdgcn_global_load_lds((const unsigned*)((const char*)(gbase) + (voff)[_i]), (PG8_LAS unsigned*)(lds + (bufoff) + ldsw + _i * 8192), 16, 0, 0); } while (0)
; #define PG8_LDA(dst, b, h) do { _Pragma("unroll") for (int m = 0; m < 4; ++m) _Pragma("unroll") for (int k = 0; k < 2; ++k) dst[m][k] = *(const PG8_LAS bf16x8*)(lds + PG8_SA(b, h) + aoff + m * 2048 + k * 1024); } while (0)
; #define PG8_LDB(dst, b, h) do { _Pragma("unroll") for (int n = 0; n < 2; ++n) _Pragma("unroll") for (int k = 0; k < 2; ++k) dst[n][k] = *(const PG8_LAS bf16x8*)(lds + PG8_SB(b, h) + boff + n * 2048 + k * 1024); } while (0)
; #define PG8_MMA(ai, bj, At, Bt) do { __builtin_amdgcn_s_setprio(1); _Pragma("unroll") for (int m = 0; m < 4; ++m) _Pragma("unroll") for (int n = 0; n < 2; ++n) _Pragma("unroll") for (int k = 0; k < 2; ++k) \
;         acc[ai][bj][m][n] = __builtin_amdgcn_mfma_f32_16x16x32_bf16(Bt[n][k], At[m][k], acc[ai][bj][m][n], 0, 0, 0); __builtin_amdgcn_s_setprio(0); } while (0)
; #define PG8_WAIT_V(n) asm volatile("s_waitcnt vmcnt(" #n ")" ::: "memory")
; #define PG8_WAIT_L(n) asm volatile("s_waitcnt lgkmcnt(" #n ")" ::: "memory")
; #define PG8_BAR __builtin_amdgcn_s_barrier()
; #define PG8_SCHED __builtin_amdgcn_sched_barrier(0)
; template <class Epi, class Sched, bool ALIGN_EPI = false, bool SP2 = false>
; __device__ __forceinline__ void gemm_phase(PG8_LAS unsigned char* lds, const Gemm g, const Sched& S, const Epi& E) {
;     ...
;             PG8_LDB(B0, 0, 0); PG8_LDB(B1, 0, 1); PG8_SCHED; PG8_LDA(At, 0, 0); PG8_STAGE(PG8_SA(1, 1), a1 + hstep, voffA);
;             PG8_WAIT_V(8); PG8_WAIT_L(0); PG8_BAR; PG8_MMA(0, 0, At, B0); PG8_MMA(0, 1, At, B1); PG8_BAR; PG8_SCHED;
;             PG8_LDA(At, 0, 1); PG8_STAGE(PG8_SB(0, 0), b2, voffB); PG8_STAGE(PG8_SB(0, 1), b2 + hstep, voffB); PG8_STAGE(PG8_SA(0, 0), a2, voffA);
;             PG8_WAIT_V(8); PG8_WAIT_L(0); PG8_BAR; PG8_MMA(1, 0, At, B0); PG8_MMA(1, 1, At, B1); PG8_BAR; PG8_SCHED;
.LBB0_2096:
	ds_read_b128 v[178:181], v175 offset:16384
	ds_read_b128 v[204:207], v175 offset:17408
	ds_read_b128 v[208:211], v175 offset:18432
	ds_read_b128 v[212:215], v175 offset:19456
	s_add_i32 m0, s55, 0xc000
	ds_read_b128 v[216:219], v177
	ds_read_b128 v[220:223], v177 offset:1024
	ds_read_b128 v[224:227], v177 offset:2048
	ds_read_b128 v[228:231], v177 offset:3072
	ds_read_b128 v[232:235], v177 offset:4096
	ds_read_b128 v[236:239], v177 offset:5120
	ds_read_b128 v[240:243], v177 offset:6144
	ds_read_b128 v[244:247], v177 offset:7168
	global_load_lds_dwordx4 v150, s[40:41]
	s_add_i32 m0, s55, 0xe000
	s_nop 0
	global_load_lds_dwordx4 v152, s[40:41]
	s_waitcnt vmcnt(8) lgkmcnt(0)
	s_setprio 0
	s_barrier
	v_mfma_f32_16x16x32_bf16 v[130:133], v[134:137], v[216:219], v[130:133]
	v_mfma_f32_16x16x32_bf16 v[126:129], v[154:157], v[216:219], v[126:129]
	v_mfma_f32_16x16x32_bf16 v[122:125], v[134:137], v[224:227], v[122:125]
	v_mfma_f32_16x16x32_bf16 v[118:121], v[154:157], v[224:227], v[118:121]
	v_mfma_f32_16x16x32_bf16 v[114:117], v[134:137], v[232:235], v[114:117]
	v_mfma_f32_16x16x32_bf16 v[110:113], v[154:157], v[232:235], v[110:113]
	v_mfma_f32_16x16x32_bf16 v[106:109], v[134:137], v[240:243], v[106:109]
	v_mfma_f32_16x16x32_bf16 v[102:105], v[154:157], v[240:243], v[102:105]
	v_mfma_f32_16x16x32_bf16 v[130:133], v[138:141], v[220:223], v[130:133]
	v_mfma_f32_16x16x32_bf16 v[126:129], v[158:161], v[220:223], v[126:129]
	v_mfma_f32_16x16x32_bf16 v[122:125], v[138:141], v[228:231], v[122:125]
	v_mfma_f32_16x16x32_bf16 v[118:121], v[158:161], v[228:231], v[118:121]
	v_mfma_f32_16x16x32_bf16 v[114:117], v[138:141], v[236:239], v[114:117]
	v_mfma_f32_16x16x32_bf16 v[110:113], v[158:161], v[236:239], v[110:113]
	v_mfma_f32_16x16x32_bf16 v[106:109], v[138:141], v[244:247], v[106:109]
	v_mfma_f32_16x16x32_bf16 v[102:105], v[158:161], v[244:247], v[102:105]
	v_mfma_f32_16x16x32_bf16 v[98:101], v[178:181], v[216:219], v[98:101]
	v_mfma_f32_16x16x32_bf16 v[94:97], v[208:211], v[216:219], v[94:97]
	v_mfma_f32_16x16x32_bf16 v[90:93], v[178:181], v[224:227], v[90:93]
	v_mfma_f32_16x16x32_bf16 v[86:89], v[208:211], v[224:227], v[86:89]
	v_mfma_f32_16x16x32_bf16 v[82:85], v[178:181], v[232:235], v[82:85]
	v_mfma_f32_16x16x32_bf16 v[78:81], v[208:211], v[232:235], v[78:81]
	v_mfma_f32_16x16x32_bf16 v[74:77], v[178:181], v[240:243], v[74:77]
	v_mfma_f32_16x16x32_bf16 v[70:73], v[208:211], v[240:243], v[70:73]
	v_mfma_f32_16x16x32_bf16 v[98:101], v[204:207], v[220:223], v[98:101]
	v_mfma_f32_16x16x32_bf16 v[94:97], v[212:215], v[220:223], v[94:97]
	v_mfma_f32_16x16x32_bf16 v[90:93], v[204:207], v[228:231], v[90:93]
	v_mfma_f32_16x16x32_bf16 v[86:89], v[212:215], v[228:231], v[86:89]
	v_mfma_f32_16x16x32_bf16 v[82:85], v[204:207], v[236:239], v[82:85]
	v_mfma_f32_16x16x32_bf16 v[78:81], v[212:215], v[236:239], v[78:81]
	v_mfma_f32_16x16x32_bf16 v[74:77], v[204:207], v[244:247], v[74:77]
	v_mfma_f32_16x16x32_bf16 v[70:73], v[212:215], v[244:247], v[70:73]
	s_setprio 3
	s_barrier
	s_add_i32 s29, s31, s54
	s_mov_b32 m0, s29
	ds_read_b128 v[216:219], v177 offset:16384
	ds_read_b128 v[220:223], v177 offset:17408
	ds_read_b128 v[224:227], v177 offset:18432
	ds_read_b128 v[228:231], v177 offset:19456
	ds_read_b128 v[232:235], v177 offset:20480
	ds_read_b128 v[236:239], v177 offset:21504
	ds_read_b128 v[240:243], v177 offset:22528
	ds_read_b128 v[244:247], v177 offset:23552
	global_load_lds_dwordx4 v144, s[42:43]
	s_add_i32 m0, s29, 0x2000
	s_add_u32 s64, s42, 0x40000
	s_addc_u32 s65, s43, 0
	s_add_i32 s27, s27, s54
	global_load_lds_dwordx4 v148, s[42:43]
	s_mov_b32 m0, s27
	s_nop 0
	global_load_lds_dwordx4 v144, s[64:65]
	s_add_i32 m0, s27, 0x2000
	s_nop 0
	global_load_lds_dwordx4 v148, s[64:65]
	s_mov_b32 m0, s55
	s_nop 0
	global_load_lds_dwordx4 v142, s[44:45]
	s_mov_b32 m0, s56
	s_nop 0
	global_load_lds_dwordx4 v146, s[44:45]
	s_waitcnt vmcnt(8) lgkmcnt(0)
	s_setprio 0
	s_barrier
	v_mfma_f32_16x16x32_bf16 v[66:69], v[134:137], v[216:219], v[66:69]
	v_mfma_f32_16x16x32_bf16 v[62:65], v[154:157], v[216:219], v[62:65]
	v_mfma_f32_16x16x32_bf16 v[58:61], v[134:137], v[224:227], v[58:61]
	v_mfma_f32_16x16x32_bf16 v[54:57], v[154:157], v[224:227], v[54:57]
	v_mfma_f32_16x16x32_bf16 v[50:53], v[134:137], v[232:235], v[50:53]
	v_mfma_f32_16x16x32_bf16 v[46:49], v[154:157], v[232:235], v[46:49]
	v_mfma_f32_16x16x32_bf16 v[42:45], v[134:137], v[240:243], v[42:45]
	v_mfma_f32_16x16x32_bf16 v[38:41], v[154:157], v[240:243], v[38:41]
	v_mfma_f32_16x16x32_bf16 v[66:69], v[138:141], v[220:223], v[66:69]
	v_mfma_f32_16x16x32_bf16 v[62:65], v[158:161], v[220:223], v[62:65]
	v_mfma_f32_16x16x32_bf16 v[58:61], v[138:141], v[228:231], v[58:61]
	v_mfma_f32_16x16x32_bf16 v[54:57], v[158:161], v[228:231], v[54:57]
	v_mfma_f32_16x16x32_bf16 v[50:53], v[138:141], v[236:239], v[50:53]
	v_mfma_f32_16x16x32_bf16 v[46:49], v[158:161], v[236:239], v[46:49]
	v_mfma_f32_16x16x32_bf16 v[42:45], v[138:141], v[244:247], v[42:45]
	v_mfma_f32_16x16x32_bf16 v[38:41], v[158:161], v[244:247], v[38:41]
	v_mfma_f32_16x16x32_bf16 v[34:37], v[178:181], v[216:219], v[34:37]
	ds_read_b128 v[134:137], v175 offset:32768
	v_mfma_f32_16x16x32_bf16 v[30:33], v[208:211], v[216:219], v[30:33]
	ds_read_b128 v[138:141], v175 offset:33792
	v_mfma_f32_16x16x32_bf16 v[26:29], v[178:181], v[224:227], v[26:29]
	ds_read_b128 v[154:157], v175 offset:34816
	v_mfma_f32_16x16x32_bf16 v[22:25], v[208:211], v[224:227], v[22:25]
	ds_read_b128 v[158:161], v175 offset:35840
	v_mfma_f32_16x16x32_bf16 v[18:21], v[178:181], v[232:235], v[18:21]
	v_mfma_f32_16x16x32_bf16 v[14:17], v[208:211], v[232:235], v[14:17]
	v_mfma_f32_16x16x32_bf16 v[10:13], v[178:181], v[240:243], v[10:13]
	v_mfma_f32_16x16x32_bf16 v[4:7], v[208:211], v[240:243], v[6:9]
	v_mfma_f32_16x16x32_bf16 v[34:37], v[204:207], v[220:223], v[34:37]
	v_mfma_f32_16x16x32_bf16 v[30:33], v[212:215], v[220:223], v[30:33]
	v_mfma_f32_16x16x32_bf16 v[26:29], v[204:207], v[228:231], v[26:29]
	v_mfma_f32_16x16x32_bf16 v[22:25], v[212:215], v[228:231], v[22:25]
	v_mfma_f32_16x16x32_bf16 v[18:21], v[204:207], v[236:239], v[18:21]
	v_mfma_f32_16x16x32_bf16 v[14:17], v[212:215], v[236:239], v[14:17]
	v_mfma_f32_16x16x32_bf16 v[10:13], v[204:207], v[244:247], v[10:13]
	v_mfma_f32_16x16x32_bf16 v[4:7], v[212:215], v[244:247], v[4:7]
	s_setprio 3
	s_barrier
; #define PG8_STAGE(bufoff, gbase, voff) do { _Pragma("unroll") for (int _i = 0; _i < 2; ++_i) \
;         __builtin_amdgcn_global_load_lds((const unsigned*)((const char*)(gbase) + (voff)[_i]), (PG8_LAS unsigned*)(lds + (bufoff) + ldsw + _i * 8192), 16, 0, 0); } while (0)
; #define PG8_LDA(dst, b, h) do { _Pragma("unroll") for (int m = 0; m < 4; ++m) _Pragma("unroll") for (int k = 0; k < 2; ++k) dst[m][k] = *(const PG8_LAS bf16x8*)(lds + PG8_SA(b, h) + aoff + m * 2048 + k * 1024); } while (0)
; #define PG8_LDB(dst, b, h) do { _Pragma("unroll") for (int n = 0; n < 2; ++n) _Pragma("unroll") for (int k = 0; k < 2; ++k) dst[n][k] = *(const PG8_LAS bf16x8*)(lds + PG8_SB(b, h) + boff + n * 2048 + k * 1024); } while (0)
; template <class Epi, class Sched, bool ALIGN_EPI = false, bool SP2 = false>
; __device__ __forceinline__ void gemm_phase(PG8_LAS unsigned char* lds, const Gemm g, const Sched& S, const Epi& E) {
;     ...
;         for (int t = 0; t < nt; t += 2) {
;             const bool last = (t == nt - 2);
;             const char* a1 = cA + (size_t)(t + 1) * kstep;
;             const char* a2 = last ? nA : cA + (size_t)(t + 2) * kstep; const char* b2 = last ? nB : cB + (size_t)(t + 2) * kstep;
;             const char* a3 = a2 + kstep; const char* b3 = b2 + kstep;
;             if (last && has_next) S.a_ready(nxt);
;             if constexpr (SP2) {
;             PG8_LDB(B0, 0, 0); PG8_LDB(B1, 0, 1); PG8_SCHED; PG8_LDA(At, 0, 0); PG8_STAGE(PG8_SA(1, 1), a1 + hstep, voffA);
;             PG8_WAIT_V(8); PG8_WAIT_L(0); PG8_BAR; PG8_MMA(0, 0, At, B0); PG8_MMA(0, 1, At, B1); PG8_BAR; PG8_SCHED;
;             PG8_LDA(At, 0, 1); PG8_STAGE(PG8_SB(0, 0), b2, voffB); PG8_STAGE(PG8_SB(0, 1), b2 + hstep, voffB); PG8_STAGE(PG8_SA(0, 0), a2, voffA);
;             PG8_WAIT_V(8); PG8_WAIT_L(0); PG8_BAR; PG8_MMA(1, 0, At, B0); PG8_MMA(1, 1, At, B1); PG8_BAR; PG8_SCHED;
;             PG8_LDB(B0, 1, 0); PG8_LDB(B1, 1, 1); PG8_SCHED; PG8_LDA(At, 1, 0); PG8_STAGE(PG8_SA(0, 1), a2 + hstep, voffA);
;             PG8_WAIT_V(8); PG8_WAIT_L(0); PG8_BAR; PG8_MMA(0, 0, At, B0); PG8_MMA(0, 1, At, B1); PG8_BAR; PG8_SCHED;
;             PG8_LDA(At, 1, 1); PG8_STAGE(PG8_SB(1, 0), b3, voffB); PG8_STAGE(PG8_SB(1, 1), b3 + hstep, voffB); PG8_STAGE(PG8_SA(1, 0), a3, voffA);
;             PG8_WAIT_V(8); PG8_WAIT_L(0); PG8_BAR; PG8_MMA(1, 0, At, B0); PG8_MMA(1, 1, At, B1); PG8_BAR; PG8_SCHED;
	s_add_i32 s27, 0, 0x18000
	s_add_i32 s29, 0, 0x1c000
	ds_read_b128 v[178:181], v175 offset:49152
	ds_read_b128 v[204:207], v175 offset:50176
	ds_read_b128 v[208:211], v175 offset:51200
	ds_read_b128 v[212:215], v175 offset:52224
	s_add_u32 s100, s44, 0x80
	s_addc_u32 s101, s45, 0
	s_add_u32 s44, s44, 0x40000
	s_addc_u32 s45, s45, 0
	s_mov_b32 m0, s57
	ds_read_b128 v[216:219], v177 offset:32768
	ds_read_b128 v[220:223], v177 offset:33792
	ds_read_b128 v[224:227], v177 offset:34816
	ds_read_b128 v[228:231], v177 offset:35840
	ds_read_b128 v[232:235], v177 offset:36864
	ds_read_b128 v[236:239], v177 offset:37888
	ds_read_b128 v[240:243], v177 offset:38912
	ds_read_b128 v[244:247], v177 offset:39936
	global_load_lds_dwordx4 v142, s[44:45]
	s_mov_b32 m0, s58
	s_nop 0
	global_load_lds_dwordx4 v146, s[44:45]
	s_waitcnt vmcnt(8) lgkmcnt(0)
	s_setprio 0
	s_barrier
	v_mfma_f32_16x16x32_bf16 v[130:133], v[134:137], v[216:219], v[130:133]
	v_mfma_f32_16x16x32_bf16 v[126:129], v[154:157], v[216:219], v[126:129]
	v_mfma_f32_16x16x32_bf16 v[122:125], v[134:137], v[224:227], v[122:125]
	v_mfma_f32_16x16x32_bf16 v[118:121], v[154:157], v[224:227], v[118:121]
	v_mfma_f32_16x16x32_bf16 v[114:117], v[134:137], v[232:235], v[114:117]
	v_mfma_f32_16x16x32_bf16 v[110:113], v[154:157], v[232:235], v[110:113]
	v_mfma_f32_16x16x32_bf16 v[106:109], v[134:137], v[240:243], v[106:109]
	v_mfma_f32_16x16x32_bf16 v[102:105], v[154:157], v[240:243], v[102:105]
	v_mfma_f32_16x16x32_bf16 v[130:133], v[138:141], v[220:223], v[130:133]
	v_mfma_f32_16x16x32_bf16 v[126:129], v[158:161], v[220:223], v[126:129]
	v_mfma_f32_16x16x32_bf16 v[122:125], v[138:141], v[228:231], v[122:125]
	v_mfma_f32_16x16x32_bf16 v[118:121], v[158:161], v[228:231], v[118:121]
	v_mfma_f32_16x16x32_bf16 v[114:117], v[138:141], v[236:239], v[114:117]
	v_mfma_f32_16x16x32_bf16 v[110:113], v[158:161], v[236:239], v[110:113]
	v_mfma_f32_16x16x32_bf16 v[106:109], v[138:141], v[244:247], v[106:109]
	v_mfma_f32_16x16x32_bf16 v[102:105], v[158:161], v[244:247], v[102:105]
	v_mfma_f32_16x16x32_bf16 v[98:101], v[178:181], v[216:219], v[98:101]
	v_mfma_f32_16x16x32_bf16 v[94:97], v[208:211], v[216:219], v[94:97]
	v_mfma_f32_16x16x32_bf16 v[90:93], v[178:181], v[224:227], v[90:93]
	v_mfma_f32_16x16x32_bf16 v[86:89], v[208:211], v[224:227], v[86:89]
	v_mfma_f32_16x16x32_bf16 v[82:85], v[178:181], v[232:235], v[82:85]
	v_mfma_f32_16x16x32_bf16 v[78:81], v[208:211], v[232:235], v[78:81]
	v_mfma_f32_16x16x32_bf16 v[74:77], v[178:181], v[240:243], v[74:77]
	v_mfma_f32_16x16x32_bf16 v[70:73], v[208:211], v[240:243], v[70:73]
	v_mfma_f32_16x16x32_bf16 v[98:101], v[204:207], v[220:223], v[98:101]
	v_mfma_f32_16x16x32_bf16 v[94:97], v[212:215], v[220:223], v[94:97]
	v_mfma_f32_16x16x32_bf16 v[90:93], v[204:207], v[228:231], v[90:93]
	v_mfma_f32_16x16x32_bf16 v[86:89], v[212:215], v[228:231], v[86:89]
	v_mfma_f32_16x16x32_bf16 v[82:85], v[204:207], v[236:239], v[82:85]
	v_mfma_f32_16x16x32_bf16 v[78:81], v[212:215], v[236:239], v[78:81]
	v_mfma_f32_16x16x32_bf16 v[74:77], v[204:207], v[244:247], v[74:77]
	v_mfma_f32_16x16x32_bf16 v[70:73], v[212:215], v[244:247], v[70:73]
	s_setprio 3
	s_barrier
	s_add_i32 s27, s27, s54
	s_add_i32 m0, s27, 0xffffff80
	ds_read_b128 v[216:219], v177 offset:49152
	ds_read_b128 v[220:223], v177 offset:50176
	ds_read_b128 v[224:227], v177 offset:51200
	ds_read_b128 v[228:231], v177 offset:52224
	ds_read_b128 v[232:235], v177 offset:53248
	ds_read_b128 v[236:239], v177 offset:54272
	ds_read_b128 v[240:243], v177 offset:55296
	ds_read_b128 v[244:247], v177 offset:56320
	global_load_lds_dwordx4 v144, s[42:43] offset:128
	s_add_i32 m0, s27, 0x1f80
	s_add_i32 s27, s29, s54
	global_load_lds_dwordx4 v148, s[42:43] offset:128
	s_add_u32 s42, s42, 0x40080
	s_addc_u32 s43, s43, 0
	s_mov_b32 m0, s27
	s_nop 0
	global_load_lds_dwordx4 v144, s[42:43]
	s_add_i32 m0, s27, 0x2000
	s_nop 0
	global_load_lds_dwordx4 v148, s[42:43]
	s_mov_b32 m0, s61
	s_nop 0
	global_load_lds_dwordx4 v142, s[100:101]
	s_mov_b32 m0, s62
	s_nop 0
	global_load_lds_dwordx4 v146, s[100:101]
	s_nop 0
	s_waitcnt vmcnt(8) lgkmcnt(0)
	s_setprio 0
	s_barrier
	v_mfma_f32_16x16x32_bf16 v[66:69], v[134:137], v[216:219], v[66:69]
	v_mfma_f32_16x16x32_bf16 v[62:65], v[154:157], v[216:219], v[62:65]
	v_mfma_f32_16x16x32_bf16 v[58:61], v[134:137], v[224:227], v[58:61]
	v_mfma_f32_16x16x32_bf16 v[54:57], v[154:157], v[224:227], v[54:57]
	v_mfma_f32_16x16x32_bf16 v[50:53], v[134:137], v[232:235], v[50:53]
	v_mfma_f32_16x16x32_bf16 v[46:49], v[154:157], v[232:235], v[46:49]
	v_mfma_f32_16x16x32_bf16 v[42:45], v[134:137], v[240:243], v[42:45]
	v_mfma_f32_16x16x32_bf16 v[38:41], v[154:157], v[240:243], v[38:41]
	v_mfma_f32_16x16x32_bf16 v[66:69], v[138:141], v[220:223], v[66:69]
	v_mfma_f32_16x16x32_bf16 v[62:65], v[158:161], v[220:223], v[62:65]
	v_mfma_f32_16x16x32_bf16 v[58:61], v[138:141], v[228:231], v[58:61]
	v_mfma_f32_16x16x32_bf16 v[54:57], v[158:161], v[228:231], v[54:57]
	v_mfma_f32_16x16x32_bf16 v[50:53], v[138:141], v[236:239], v[50:53]
	v_mfma_f32_16x16x32_bf16 v[46:49], v[158:161], v[236:239], v[46:49]
	v_mfma_f32_16x16x32_bf16 v[42:45], v[138:141], v[244:247], v[42:45]
	v_mfma_f32_16x16x32_bf16 v[38:41], v[158:161], v[244:247], v[38:41]
	v_mfma_f32_16x16x32_bf16 v[34:37], v[178:181], v[216:219], v[34:37]
	ds_read_b128 v[134:137], v175
	v_mfma_f32_16x16x32_bf16 v[30:33], v[208:211], v[216:219], v[30:33]
	ds_read_b128 v[138:141], v175 offset:1024
	v_mfma_f32_16x16x32_bf16 v[26:29], v[178:181], v[224:227], v[26:29]
	ds_read_b128 v[154:157], v175 offset:2048
	v_mfma_f32_16x16x32_bf16 v[22:25], v[208:211], v[224:227], v[22:25]
	ds_read_b128 v[158:161], v175 offset:3072
	v_mfma_f32_16x16x32_bf16 v[18:21], v[178:181], v[232:235], v[18:21]
	v_mfma_f32_16x16x32_bf16 v[14:17], v[208:211], v[232:235], v[14:17]
	v_mfma_f32_16x16x32_bf16 v[8:11], v[178:181], v[240:243], v[10:13]
	v_mfma_f32_16x16x32_bf16 v[4:7], v[208:211], v[240:243], v[4:7]
	v_mfma_f32_16x16x32_bf16 v[34:37], v[204:207], v[220:223], v[34:37]
	v_mfma_f32_16x16x32_bf16 v[30:33], v[212:215], v[220:223], v[30:33]
	v_mfma_f32_16x16x32_bf16 v[26:29], v[204:207], v[228:231], v[26:29]
	v_mfma_f32_16x16x32_bf16 v[22:25], v[212:215], v[228:231], v[22:25]
	v_mfma_f32_16x16x32_bf16 v[18:21], v[204:207], v[236:239], v[18:21]
	v_mfma_f32_16x16x32_bf16 v[14:17], v[212:215], v[236:239], v[14:17]
	v_mfma_f32_16x16x32_bf16 v[10:13], v[204:207], v[244:247], v[8:11]
	v_mfma_f32_16x16x32_bf16 v[6:9], v[212:215], v[244:247], v[4:7]
	s_add_i32 s26, s26, 2
	s_add_u32 s40, s40, 0x100
	s_addc_u32 s41, s41, 0
	s_add_u32 s11, s11, 0x100
	s_addc_u32 s13, s13, 0
	s_add_u32 s27, s40, 0xfffc0080
	s_addc_u32 s29, s41, -1
	s_add_i32 s31, 0, 0x10000
	s_cmp_eq_u32 s26, 12
	s_cselect_b32 s45, s1, s29
	s_cselect_b32 s44, s0, s27
	s_cselect_b32 s43, s35, s13
	s_cselect_b32 s42, s34, s11
	s_add_i32 s27, 0, 0x14000
	s_setprio 3
	s_barrier
	s_cmp_gt_u32 s26, 13
	s_cbranch_scc0 .LBB0_2096
	s_and_b64 vcc, exec, s[8:9]
	s_cbranch_vccz .LBB0_2099
	s_barrier

; #define PG8_STAGE(bufoff, gbase, voff) do { _Pragma("unroll") for (int _i = 0; _i < 2; ++_i) \
;         __builtin_amdgcn_global_load_lds((const unsigned*)((const char*)(gbase) + (voff)[_i]), (PG8_LAS unsigned*)(lds + (bufoff) + ldsw + _i * 8192), 16, 0, 0); } while (0)
; #define PG8_LDA(dst, b, h) do { _Pragma("unroll") for (int m = 0; m < 4; ++m) _Pragma("unroll") for (int k = 0; k < 2; ++k) dst[m][k] = *(const PG8_LAS bf16x8*)(lds + PG8_SA(b, h) + aoff + m * 2048 + k * 1024); } while (0)
; #define PG8_LDB(dst, b, h) do { _Pragma("unroll") for (int n = 0; n < 2; ++n) _Pragma("unroll") for (int k = 0; k < 2; ++k) dst[n][k] = *(const PG8_LAS bf16x8*)(lds + PG8_SB(b, h) + boff + n * 2048 + k * 1024); } while (0)
; #define PG8_MMA(ai, bj, At, Bt) do { __builtin_amdgcn_s_setprio(1); _Pragma("unroll") for (int m = 0; m < 4; ++m) _Pragma("unroll") for (int n = 0; n < 2; ++n) _Pragma("unroll") for (int k = 0; k < 2; ++k) \
;         acc[ai][bj][m][n] = __builtin_amdgcn_mfma_f32_16x16x32_bf16(Bt[n][k], At[m][k], acc[ai][bj][m][n], 0, 0, 0); __builtin_amdgcn_s_setprio(0); } while (0)
; #define PG8_WAIT_V(n) asm volatile("s_waitcnt vmcnt(" #n ")" ::: "memory")
; #define PG8_BAR __builtin_amdgcn_s_barrier()
; template <class Epi, class Sched, bool ALIGN_EPI = false, bool SP2 = false>
; __device__ __forceinline__ void gemm_phase(PG8_LAS unsigned char* lds, const Gemm g, const Sched& S, const Epi& E) {
;     ...
;         for (int t = 0; t < nt; t += 2) {
;             const bool last = (t == nt - 2);
;             const char* a1 = cA + (size_t)(t + 1) * kstep;
;             const char* a2 = last ? nA : cA + (size_t)(t + 2) * kstep; const char* b2 = last ? nB : cB + (size_t)(t + 2) * kstep;
;             const char* a3 = a2 + kstep; const char* b3 = b2 + kstep;
;             if (last && has_next) S.a_ready(nxt);
;             if constexpr (SP2) {
;             PG8_LDB(B0, 0, 0); PG8_LDB(B1, 0, 1); PG8_SCHED; PG8_LDA(At, 0, 0); PG8_STAGE(PG8_SA(1, 1), a1 + hstep, voffA);
;             PG8_WAIT_V(8); PG8_WAIT_L(0); PG8_BAR; PG8_MMA(0, 0, At, B0); PG8_MMA(0, 1, At, B1); PG8_BAR; PG8_SCHED;
;             PG8_LDA(At, 0, 1); PG8_STAGE(PG8_SB(0, 0), b2, voffB); PG8_STAGE(PG8_SB(0, 1), b2 + hstep, voffB); PG8_STAGE(PG8_SA(0, 0), a2, voffA);
;             PG8_WAIT_V(8); PG8_WAIT_L(0); PG8_BAR; PG8_MMA(1, 0, At, B0); PG8_MMA(1, 1, At, B1); PG8_BAR; PG8_SCHED;
.LBB0_2185:
	ds_read_b128 v[158:161], v243 offset:16384
	ds_read_b128 v[174:177], v243 offset:17408
	ds_read_b128 v[180:183], v243 offset:18432
	ds_read_b128 v[204:207], v243 offset:19456
	v_lshl_add_u64 v[162:163], s[40:41], 0, v[138:139]
	s_add_i32 m0, s55, 0xc000
	ds_read_b128 v[208:211], v179
	ds_read_b128 v[212:215], v179 offset:1024
	ds_read_b128 v[216:219], v179 offset:2048
	ds_read_b128 v[220:223], v179 offset:3072
	ds_read_b128 v[224:227], v179 offset:4096
	ds_read_b128 v[228:231], v179 offset:5120
	ds_read_b128 v[232:235], v179 offset:6144
	ds_read_b128 v[236:239], v179 offset:7168
	global_load_lds_dwordx4 v[162:163], off
	v_lshl_add_u64 v[162:163], s[40:41], 0, v[140:141]
	s_add_i32 m0, s55, 0xe000
	s_nop 0
	global_load_lds_dwordx4 v[162:163], off
	s_waitcnt vmcnt(8) lgkmcnt(0)
	s_setprio 0
	s_barrier
	v_mfma_f32_16x16x32_bf16 v[128:131], v[142:145], v[208:211], v[128:131]
	v_mfma_f32_16x16x32_bf16 v[124:127], v[150:153], v[208:211], v[124:127]
	v_mfma_f32_16x16x32_bf16 v[112:115], v[142:145], v[216:219], v[112:115]
	v_mfma_f32_16x16x32_bf16 v[108:111], v[150:153], v[216:219], v[108:111]
	v_mfma_f32_16x16x32_bf16 v[96:99], v[142:145], v[224:227], v[96:99]
	v_mfma_f32_16x16x32_bf16 v[92:95], v[150:153], v[224:227], v[92:95]
	v_mfma_f32_16x16x32_bf16 v[80:83], v[142:145], v[232:235], v[80:83]
	v_mfma_f32_16x16x32_bf16 v[76:79], v[150:153], v[232:235], v[76:79]
	v_mfma_f32_16x16x32_bf16 v[128:131], v[146:149], v[212:215], v[128:131]
	v_mfma_f32_16x16x32_bf16 v[124:127], v[154:157], v[212:215], v[124:127]
	v_mfma_f32_16x16x32_bf16 v[112:115], v[146:149], v[220:223], v[112:115]
	v_mfma_f32_16x16x32_bf16 v[108:111], v[154:157], v[220:223], v[108:111]
	v_mfma_f32_16x16x32_bf16 v[96:99], v[146:149], v[228:231], v[96:99]
	v_mfma_f32_16x16x32_bf16 v[92:95], v[154:157], v[228:231], v[92:95]
	v_mfma_f32_16x16x32_bf16 v[80:83], v[146:149], v[236:239], v[80:83]
	v_mfma_f32_16x16x32_bf16 v[76:79], v[154:157], v[236:239], v[76:79]
	v_mfma_f32_16x16x32_bf16 v[120:123], v[158:161], v[208:211], v[120:123]
	v_mfma_f32_16x16x32_bf16 v[116:119], v[180:183], v[208:211], v[116:119]
	v_mfma_f32_16x16x32_bf16 v[104:107], v[158:161], v[216:219], v[104:107]
	v_mfma_f32_16x16x32_bf16 v[100:103], v[180:183], v[216:219], v[100:103]
	v_mfma_f32_16x16x32_bf16 v[88:91], v[158:161], v[224:227], v[88:91]
	v_mfma_f32_16x16x32_bf16 v[84:87], v[180:183], v[224:227], v[84:87]
	v_mfma_f32_16x16x32_bf16 v[72:75], v[158:161], v[232:235], v[72:75]
	v_mfma_f32_16x16x32_bf16 v[68:71], v[180:183], v[232:235], v[68:71]
	v_mfma_f32_16x16x32_bf16 v[120:123], v[174:177], v[212:215], v[120:123]
	v_mfma_f32_16x16x32_bf16 v[116:119], v[204:207], v[212:215], v[116:119]
	v_mfma_f32_16x16x32_bf16 v[104:107], v[174:177], v[220:223], v[104:107]
	v_mfma_f32_16x16x32_bf16 v[100:103], v[204:207], v[220:223], v[100:103]
	v_mfma_f32_16x16x32_bf16 v[88:91], v[174:177], v[228:231], v[88:91]
	v_mfma_f32_16x16x32_bf16 v[84:87], v[204:207], v[228:231], v[84:87]
	v_mfma_f32_16x16x32_bf16 v[72:75], v[174:177], v[236:239], v[72:75]
	v_mfma_f32_16x16x32_bf16 v[68:71], v[204:207], v[236:239], v[68:71]
	s_setprio 3
	s_barrier
	s_add_i32 s37, s37, s54
	s_mov_b32 m0, s37
	ds_read_b128 v[208:211], v179 offset:16384
	ds_read_b128 v[212:215], v179 offset:17408
	ds_read_b128 v[216:219], v179 offset:18432
	ds_read_b128 v[220:223], v179 offset:19456
	ds_read_b128 v[224:227], v179 offset:20480
	ds_read_b128 v[228:231], v179 offset:21504
	ds_read_b128 v[232:235], v179 offset:22528
	ds_read_b128 v[236:239], v179 offset:23552
	global_load_lds_dwordx4 v2, s[44:45]
	s_add_i32 m0, s37, 0x2000
	s_add_u32 s40, s44, 0x80000
	s_addc_u32 s41, s45, 0
	s_add_i32 s37, s39, s54
	global_load_lds_dwordx4 v132, s[44:45]
	s_mov_b32 m0, s37
	s_nop 0
	global_load_lds_dwordx4 v2, s[40:41]
	s_add_i32 m0, s37, 0x2000
	s_nop 0
	global_load_lds_dwordx4 v132, s[40:41]
	s_mov_b32 m0, s55
	s_nop 0
	global_load_lds_dwordx4 v2, s[46:47]
	s_mov_b32 m0, s56
	s_nop 0
	global_load_lds_dwordx4 v132, s[46:47]
	s_waitcnt vmcnt(8) lgkmcnt(0)
	s_setprio 0
	s_barrier
	v_mfma_f32_16x16x32_bf16 v[64:67], v[142:145], v[208:211], v[64:67]
	v_mfma_f32_16x16x32_bf16 v[60:63], v[150:153], v[208:211], v[60:63]
	v_mfma_f32_16x16x32_bf16 v[48:51], v[142:145], v[216:219], v[48:51]
	v_mfma_f32_16x16x32_bf16 v[44:47], v[150:153], v[216:219], v[44:47]
	v_mfma_f32_16x16x32_bf16 v[32:35], v[142:145], v[224:227], v[32:35]
	v_mfma_f32_16x16x32_bf16 v[28:31], v[150:153], v[224:227], v[28:31]
	v_mfma_f32_16x16x32_bf16 v[16:19], v[142:145], v[232:235], v[16:19]
	v_mfma_f32_16x16x32_bf16 v[12:15], v[150:153], v[232:235], v[12:15]
	v_mfma_f32_16x16x32_bf16 v[64:67], v[146:149], v[212:215], v[64:67]
	v_mfma_f32_16x16x32_bf16 v[60:63], v[154:157], v[212:215], v[60:63]
	v_mfma_f32_16x16x32_bf16 v[48:51], v[146:149], v[220:223], v[48:51]
	v_mfma_f32_16x16x32_bf16 v[44:47], v[154:157], v[220:223], v[44:47]
	v_mfma_f32_16x16x32_bf16 v[32:35], v[146:149], v[228:231], v[32:35]
	v_mfma_f32_16x16x32_bf16 v[28:31], v[154:157], v[228:231], v[28:31]
	v_mfma_f32_16x16x32_bf16 v[16:19], v[146:149], v[236:239], v[16:19]
	v_mfma_f32_16x16x32_bf16 v[12:15], v[154:157], v[236:239], v[12:15]
	v_mfma_f32_16x16x32_bf16 v[56:59], v[158:161], v[208:211], v[56:59]
	ds_read_b128 v[142:145], v243 offset:32768
	v_mfma_f32_16x16x32_bf16 v[52:55], v[180:183], v[208:211], v[52:55]
	ds_read_b128 v[146:149], v243 offset:33792
	v_mfma_f32_16x16x32_bf16 v[40:43], v[158:161], v[216:219], v[40:43]
	ds_read_b128 v[150:153], v243 offset:34816
	v_mfma_f32_16x16x32_bf16 v[36:39], v[180:183], v[216:219], v[36:39]
	ds_read_b128 v[154:157], v243 offset:35840
	v_mfma_f32_16x16x32_bf16 v[24:27], v[158:161], v[224:227], v[24:27]
	v_mfma_f32_16x16x32_bf16 v[20:23], v[180:183], v[224:227], v[20:23]
	v_mfma_f32_16x16x32_bf16 v[8:11], v[158:161], v[232:235], v[8:11]
	v_mfma_f32_16x16x32_bf16 v[4:7], v[180:183], v[232:235], v[4:7]
	v_mfma_f32_16x16x32_bf16 v[56:59], v[174:177], v[212:215], v[56:59]
	v_mfma_f32_16x16x32_bf16 v[52:55], v[204:207], v[212:215], v[52:55]
	v_mfma_f32_16x16x32_bf16 v[40:43], v[174:177], v[220:223], v[40:43]
	v_mfma_f32_16x16x32_bf16 v[36:39], v[204:207], v[220:223], v[36:39]
	v_mfma_f32_16x16x32_bf16 v[24:27], v[174:177], v[228:231], v[24:27]
	v_mfma_f32_16x16x32_bf16 v[20:23], v[204:207], v[228:231], v[20:23]
	v_mfma_f32_16x16x32_bf16 v[8:11], v[174:177], v[236:239], v[8:11]
	v_mfma_f32_16x16x32_bf16 v[4:7], v[204:207], v[236:239], v[4:7]
	s_setprio 3
	s_barrier
; #define PG8_STAGE(bufoff, gbase, voff) do { _Pragma("unroll") for (int _i = 0; _i < 2; ++_i) \
;         __builtin_amdgcn_global_load_lds((const unsigned*)((const char*)(gbase) + (voff)[_i]), (PG8_LAS unsigned*)(lds + (bufoff) + ldsw + _i * 8192), 16, 0, 0); } while (0)
; #define PG8_LDA(dst, b, h) do { _Pragma("unroll") for (int m = 0; m < 4; ++m) _Pragma("unroll") for (int k = 0; k < 2; ++k) dst[m][k] = *(const PG8_LAS bf16x8*)(lds + PG8_SA(b, h) + aoff + m * 2048 + k * 1024); } while (0)
; #define PG8_LDB(dst, b, h) do { _Pragma("unroll") for (int n = 0; n < 2; ++n) _Pragma("unroll") for (int k = 0; k < 2; ++k) dst[n][k] = *(const PG8_LAS bf16x8*)(lds + PG8_SB(b, h) + boff + n * 2048 + k * 1024); } while (0)
; template <class Epi, class Sched, bool ALIGN_EPI = false, bool SP2 = false>
; __device__ __forceinline__ void gemm_phase(PG8_LAS unsigned char* lds, const Gemm g, const Sched& S, const Epi& E) {
;     ...
;         for (int t = 0; t < nt; t += 2) {
;             const bool last = (t == nt - 2);
;             const char* a1 = cA + (size_t)(t + 1) * kstep;
;             const char* a2 = last ? nA : cA + (size_t)(t + 2) * kstep; const char* b2 = last ? nB : cB + (size_t)(t + 2) * kstep;
;             const char* a3 = a2 + kstep; const char* b3 = b2 + kstep;
;             if (last && has_next) S.a_ready(nxt);
;             if constexpr (SP2) {
;             PG8_LDB(B0, 0, 0); PG8_LDB(B1, 0, 1); PG8_SCHED; PG8_LDA(At, 0, 0); PG8_STAGE(PG8_SA(1, 1), a1 + hstep, voffA);
;             PG8_WAIT_V(8); PG8_WAIT_L(0); PG8_BAR; PG8_MMA(0, 0, At, B0); PG8_MMA(0, 1, At, B1); PG8_BAR; PG8_SCHED;
;             PG8_LDA(At, 0, 1); PG8_STAGE(PG8_SB(0, 0), b2, voffB); PG8_STAGE(PG8_SB(0, 1), b2 + hstep, voffB); PG8_STAGE(PG8_SA(0, 0), a2, voffA);
;             PG8_WAIT_V(8); PG8_WAIT_L(0); PG8_BAR; PG8_MMA(1, 0, At, B0); PG8_MMA(1, 1, At, B1); PG8_BAR; PG8_SCHED;
;             PG8_LDB(B0, 1, 0); PG8_LDB(B1, 1, 1); PG8_SCHED; PG8_LDA(At, 1, 0); PG8_STAGE(PG8_SA(0, 1), a2 + hstep, voffA);
;             PG8_WAIT_V(8); PG8_WAIT_L(0); PG8_BAR; PG8_MMA(0, 0, At, B0); PG8_MMA(0, 1, At, B1); PG8_BAR; PG8_SCHED;
;             PG8_LDA(At, 1, 1); PG8_STAGE(PG8_SB(1, 0), b3, voffB); PG8_STAGE(PG8_SB(1, 1), b3 + hstep, voffB); PG8_STAGE(PG8_SA(1, 0), a3, voffA);
;             PG8_WAIT_V(8); PG8_WAIT_L(0); PG8_BAR; PG8_MMA(1, 0, At, B0); PG8_MMA(1, 1, At, B1); PG8_BAR; PG8_SCHED;
	s_add_i32 s37, 0, 0x18000
	s_add_i32 s39, 0, 0x1c000
	ds_read_b128 v[158:161], v243 offset:49152
	ds_read_b128 v[174:177], v243 offset:50176
	ds_read_b128 v[180:183], v243 offset:51200
	ds_read_b128 v[204:207], v243 offset:52224
	s_add_u32 s40, s46, 0x80000
	s_addc_u32 s41, s47, 0
	s_mov_b32 m0, s57
	ds_read_b128 v[208:211], v179 offset:32768
	ds_read_b128 v[212:215], v179 offset:33792
	ds_read_b128 v[216:219], v179 offset:34816
	ds_read_b128 v[220:223], v179 offset:35840
	ds_read_b128 v[224:227], v179 offset:36864
	ds_read_b128 v[228:231], v179 offset:37888
	ds_read_b128 v[232:235], v179 offset:38912
	ds_read_b128 v[236:239], v179 offset:39936
	global_load_lds_dwordx4 v2, s[40:41]
	s_mov_b32 m0, s58
	s_nop 0
	global_load_lds_dwordx4 v132, s[40:41]
	s_nop 0
	s_waitcnt vmcnt(8) lgkmcnt(0)
	s_setprio 0
	s_barrier
	v_mfma_f32_16x16x32_bf16 v[128:131], v[142:145], v[208:211], v[128:131]
	v_mfma_f32_16x16x32_bf16 v[124:127], v[150:153], v[208:211], v[124:127]
	v_mfma_f32_16x16x32_bf16 v[112:115], v[142:145], v[216:219], v[112:115]
	v_mfma_f32_16x16x32_bf16 v[108:111], v[150:153], v[216:219], v[108:111]
	v_mfma_f32_16x16x32_bf16 v[96:99], v[142:145], v[224:227], v[96:99]
	v_mfma_f32_16x16x32_bf16 v[92:95], v[150:153], v[224:227], v[92:95]
	v_mfma_f32_16x16x32_bf16 v[80:83], v[142:145], v[232:235], v[80:83]
	v_mfma_f32_16x16x32_bf16 v[76:79], v[150:153], v[232:235], v[76:79]
	v_mfma_f32_16x16x32_bf16 v[128:131], v[146:149], v[212:215], v[128:131]
	v_mfma_f32_16x16x32_bf16 v[124:127], v[154:157], v[212:215], v[124:127]
	v_mfma_f32_16x16x32_bf16 v[112:115], v[146:149], v[220:223], v[112:115]
	v_mfma_f32_16x16x32_bf16 v[108:111], v[154:157], v[220:223], v[108:111]
	v_mfma_f32_16x16x32_bf16 v[96:99], v[146:149], v[228:231], v[96:99]
	v_mfma_f32_16x16x32_bf16 v[92:95], v[154:157], v[228:231], v[92:95]
	v_mfma_f32_16x16x32_bf16 v[80:83], v[146:149], v[236:239], v[80:83]
	v_mfma_f32_16x16x32_bf16 v[76:79], v[154:157], v[236:239], v[76:79]
	v_mfma_f32_16x16x32_bf16 v[120:123], v[158:161], v[208:211], v[120:123]
	v_mfma_f32_16x16x32_bf16 v[116:119], v[180:183], v[208:211], v[116:119]
	v_mfma_f32_16x16x32_bf16 v[104:107], v[158:161], v[216:219], v[104:107]
	v_mfma_f32_16x16x32_bf16 v[100:103], v[180:183], v[216:219], v[100:103]
	v_mfma_f32_16x16x32_bf16 v[88:91], v[158:161], v[224:227], v[88:91]
	v_mfma_f32_16x16x32_bf16 v[84:87], v[180:183], v[224:227], v[84:87]
	v_mfma_f32_16x16x32_bf16 v[72:75], v[158:161], v[232:235], v[72:75]
	v_mfma_f32_16x16x32_bf16 v[68:71], v[180:183], v[232:235], v[68:71]
	v_mfma_f32_16x16x32_bf16 v[120:123], v[174:177], v[212:215], v[120:123]
	v_mfma_f32_16x16x32_bf16 v[116:119], v[204:207], v[212:215], v[116:119]
	v_mfma_f32_16x16x32_bf16 v[104:107], v[174:177], v[220:223], v[104:107]
	v_mfma_f32_16x16x32_bf16 v[100:103], v[204:207], v[220:223], v[100:103]
	v_mfma_f32_16x16x32_bf16 v[88:91], v[174:177], v[228:231], v[88:91]
	v_mfma_f32_16x16x32_bf16 v[84:87], v[204:207], v[228:231], v[84:87]
	v_mfma_f32_16x16x32_bf16 v[72:75], v[174:177], v[236:239], v[72:75]
	v_mfma_f32_16x16x32_bf16 v[68:71], v[204:207], v[236:239], v[68:71]
	s_setprio 3
	s_barrier
	s_add_i32 s37, s37, s54
	s_add_i32 m0, s37, 0xffffff80
	ds_read_b128 v[208:211], v179 offset:49152
	ds_read_b128 v[212:215], v179 offset:50176
	ds_read_b128 v[216:219], v179 offset:51200
	ds_read_b128 v[220:223], v179 offset:52224
	ds_read_b128 v[224:227], v179 offset:53248
	ds_read_b128 v[228:231], v179 offset:54272
	ds_read_b128 v[232:235], v179 offset:55296
	ds_read_b128 v[236:239], v179 offset:56320
	global_load_lds_dwordx4 v2, s[44:45] offset:128
	s_add_i32 m0, s37, 0x1f80
	s_add_u32 s40, s44, 0x80080
	s_addc_u32 s41, s45, 0
	s_add_i32 s37, s39, s54
	global_load_lds_dwordx4 v132, s[44:45] offset:128
	s_mov_b32 m0, s37
	s_nop 0
	global_load_lds_dwordx4 v2, s[40:41]
	s_add_i32 m0, s37, 0x2000
	s_nop 0
	global_load_lds_dwordx4 v132, s[40:41]
	s_add_i32 m0, s60, 0xffffff80
	s_nop 0
	global_load_lds_dwordx4 v2, s[46:47] offset:128
	s_add_i32 m0, s61, 0xffffff80
	s_nop 0
	global_load_lds_dwordx4 v132, s[46:47] offset:128
	s_nop 0
	s_waitcnt vmcnt(8) lgkmcnt(0)
	s_setprio 0
	s_barrier
	v_mfma_f32_16x16x32_bf16 v[64:67], v[142:145], v[208:211], v[64:67]
	v_mfma_f32_16x16x32_bf16 v[60:63], v[150:153], v[208:211], v[60:63]
	v_mfma_f32_16x16x32_bf16 v[48:51], v[142:145], v[216:219], v[48:51]
	v_mfma_f32_16x16x32_bf16 v[44:47], v[150:153], v[216:219], v[44:47]
	v_mfma_f32_16x16x32_bf16 v[32:35], v[142:145], v[224:227], v[32:35]
	v_mfma_f32_16x16x32_bf16 v[28:31], v[150:153], v[224:227], v[28:31]
	v_mfma_f32_16x16x32_bf16 v[16:19], v[142:145], v[232:235], v[16:19]
	v_mfma_f32_16x16x32_bf16 v[12:15], v[150:153], v[232:235], v[12:15]
	v_mfma_f32_16x16x32_bf16 v[64:67], v[146:149], v[212:215], v[64:67]
	v_mfma_f32_16x16x32_bf16 v[60:63], v[154:157], v[212:215], v[60:63]
	v_mfma_f32_16x16x32_bf16 v[48:51], v[146:149], v[220:223], v[48:51]
	v_mfma_f32_16x16x32_bf16 v[44:47], v[154:157], v[220:223], v[44:47]
	v_mfma_f32_16x16x32_bf16 v[32:35], v[146:149], v[228:231], v[32:35]
	v_mfma_f32_16x16x32_bf16 v[28:31], v[154:157], v[228:231], v[28:31]
	v_mfma_f32_16x16x32_bf16 v[16:19], v[146:149], v[236:239], v[16:19]
	v_mfma_f32_16x16x32_bf16 v[12:15], v[154:157], v[236:239], v[12:15]
	v_mfma_f32_16x16x32_bf16 v[56:59], v[158:161], v[208:211], v[56:59]
	ds_read_b128 v[142:145], v243
	v_mfma_f32_16x16x32_bf16 v[52:55], v[180:183], v[208:211], v[52:55]
	ds_read_b128 v[146:149], v243 offset:1024
	v_mfma_f32_16x16x32_bf16 v[40:43], v[158:161], v[216:219], v[40:43]
	ds_read_b128 v[150:153], v243 offset:2048
	v_mfma_f32_16x16x32_bf16 v[36:39], v[180:183], v[216:219], v[36:39]
	ds_read_b128 v[154:157], v243 offset:3072
	v_mfma_f32_16x16x32_bf16 v[24:27], v[158:161], v[224:227], v[24:27]
	v_mfma_f32_16x16x32_bf16 v[20:23], v[180:183], v[224:227], v[20:23]
	v_mfma_f32_16x16x32_bf16 v[8:11], v[158:161], v[232:235], v[8:11]
	v_mfma_f32_16x16x32_bf16 v[4:7], v[180:183], v[232:235], v[4:7]
	v_mfma_f32_16x16x32_bf16 v[56:59], v[174:177], v[212:215], v[56:59]
	v_mfma_f32_16x16x32_bf16 v[52:55], v[204:207], v[212:215], v[52:55]
	v_mfma_f32_16x16x32_bf16 v[40:43], v[174:177], v[220:223], v[40:43]
	v_mfma_f32_16x16x32_bf16 v[36:39], v[204:207], v[220:223], v[36:39]
	v_mfma_f32_16x16x32_bf16 v[24:27], v[174:177], v[228:231], v[24:27]
	v_mfma_f32_16x16x32_bf16 v[20:23], v[204:207], v[228:231], v[20:23]
	v_mfma_f32_16x16x32_bf16 v[8:11], v[174:177], v[236:239], v[8:11]
	v_mfma_f32_16x16x32_bf16 v[4:7], v[204:207], v[236:239], v[4:7]
	s_add_i32 s31, s31, 2
	s_add_u32 s2, s2, 0x100
	s_addc_u32 s29, s29, 0
	s_mov_b64 s[40:41], s[42:43]
	s_add_u32 s42, s40, 0x100
	s_addc_u32 s43, s41, 0
	s_add_i32 s37, 0, 0x10000
	s_cmp_eq_u32 s31, 28
	s_cselect_b32 s47, s5, s43
	s_cselect_b32 s46, s4, s42
	s_cselect_b32 s45, s35, s29
	s_cselect_b32 s44, s34, s2
	s_add_i32 s39, 0, 0x14000
	s_setprio 3
	s_barrier
	s_cmp_gt_u32 s31, 29
	s_cbranch_scc0 .LBB0_2185
	s_and_b64 vcc, exec, s[26:27]
	s_cbranch_vccz .LBB0_2188
	s_barrier
